# balanced LDS-read load across K-loop phases: B0 fragment reads of phases 1/5 moved to the read-free load segments of phases 8/4 (reads per phase 12/4/8/0 -> 8/4/8/4), DMA retired one barrier earlier b
# speedup vs baseline: 1.0119x; 1.0047x over previous
.Lg131_noy:
	ds_read_b128 v[152:155], v149
	ds_read_b128 v[156:159], v149 offset:1024
	ds_read_b128 v[160:163], v149 offset:2048
	ds_read_b128 v[164:167], v149 offset:3072
	s_add_u32 s26, s20, 0xfffc0080
	s_addc_u32 s27, s21, -1
	s_cmp_eq_u32 s57, 12
	s_cselect_b32 s29, s13, s27
	s_cselect_b32 s28, s53, s26
	s_cselect_b32 s27, s11, s56
	s_cselect_b32 s26, s54, s55
	s_add_i32 m0, s19, 0xc000
	ds_read_b128 v[168:171], v150
	ds_read_b128 v[172:175], v150 offset:1024
	ds_read_b128 v[176:179], v150 offset:2048
	ds_read_b128 v[180:183], v150 offset:3072
	ds_read_b128 v[184:187], v150 offset:4096
	ds_read_b128 v[188:191], v150 offset:5120
	ds_read_b128 v[192:195], v150 offset:6144
	ds_read_b128 v[196:199], v150 offset:7168
	global_load_lds_dwordx4 v136, s[20:21]
	s_add_i32 m0, s19, 0xe000
	s_nop 0
	global_load_lds_dwordx4 v138, s[20:21]
	s_waitcnt lgkmcnt(8)
	s_barrier
	s_waitcnt lgkmcnt(0)
	s_waitcnt lgkmcnt(0)
	v_mfma_f32_16x16x32_bf16 v[124:127], v[152:155], v[168:171], 0
	v_mfma_f32_16x16x32_bf16 v[120:123], v[160:163], v[168:171], 0
	v_mfma_f32_16x16x32_bf16 v[108:111], v[152:155], v[176:179], 0
	v_mfma_f32_16x16x32_bf16 v[104:107], v[160:163], v[176:179], 0
	v_mfma_f32_16x16x32_bf16 v[92:95], v[152:155], v[184:187], 0
	v_mfma_f32_16x16x32_bf16 v[88:91], v[160:163], v[184:187], 0
	v_mfma_f32_16x16x32_bf16 v[76:79], v[152:155], v[192:195], 0
	v_mfma_f32_16x16x32_bf16 v[72:75], v[160:163], v[192:195], 0
	v_mfma_f32_16x16x32_bf16 v[124:127], v[156:159], v[172:175], v[124:127]
	v_mfma_f32_16x16x32_bf16 v[120:123], v[164:167], v[172:175], v[120:123]
	v_mfma_f32_16x16x32_bf16 v[108:111], v[156:159], v[180:183], v[108:111]
	v_mfma_f32_16x16x32_bf16 v[104:107], v[164:167], v[180:183], v[104:107]
	v_mfma_f32_16x16x32_bf16 v[92:95], v[156:159], v[188:191], v[92:95]
	v_mfma_f32_16x16x32_bf16 v[88:91], v[164:167], v[188:191], v[88:91]
	v_mfma_f32_16x16x32_bf16 v[76:79], v[156:159], v[196:199], v[76:79]
	v_mfma_f32_16x16x32_bf16 v[72:75], v[164:167], v[196:199], v[72:75]
	s_barrier
	s_add_i32 s58, s47, s38
	s_add_u32 s80, s26, 0x80
	s_addc_u32 s81, s27, 0
	s_mov_b32 m0, s58
	ds_read_b128 v[200:203], v151
	ds_read_b128 v[204:207], v151 offset:1024
	ds_read_b128 v[208:211], v151 offset:2048
	ds_read_b128 v[212:215], v151 offset:3072
	global_load_lds_dwordx4 v132, s[26:27]
	s_add_i32 m0, s58, 0x2000
	s_nop 0
	global_load_lds_dwordx4 v128, s[26:27]
	s_waitcnt vmcnt(10)
	s_barrier
	s_waitcnt lgkmcnt(0)
	s_waitcnt lgkmcnt(0)
	v_mfma_f32_16x16x32_bf16 v[116:119], v[200:203], v[168:171], 0
	v_mfma_f32_16x16x32_bf16 v[112:115], v[208:211], v[168:171], 0
	v_mfma_f32_16x16x32_bf16 v[100:103], v[200:203], v[176:179], 0
	v_mfma_f32_16x16x32_bf16 v[96:99], v[208:211], v[176:179], 0
	v_mfma_f32_16x16x32_bf16 v[84:87], v[200:203], v[184:187], 0
	v_mfma_f32_16x16x32_bf16 v[80:83], v[208:211], v[184:187], 0
	v_mfma_f32_16x16x32_bf16 v[68:71], v[200:203], v[192:195], 0
	v_mfma_f32_16x16x32_bf16 v[64:67], v[208:211], v[192:195], 0
	v_mfma_f32_16x16x32_bf16 v[116:119], v[204:207], v[172:175], v[116:119]
	v_mfma_f32_16x16x32_bf16 v[112:115], v[212:215], v[172:175], v[112:115]
	v_mfma_f32_16x16x32_bf16 v[100:103], v[204:207], v[180:183], v[100:103]
	v_mfma_f32_16x16x32_bf16 v[96:99], v[212:215], v[180:183], v[96:99]
	v_mfma_f32_16x16x32_bf16 v[84:87], v[204:207], v[188:191], v[84:87]
	v_mfma_f32_16x16x32_bf16 v[80:83], v[212:215], v[188:191], v[80:83]
	v_mfma_f32_16x16x32_bf16 v[68:71], v[204:207], v[196:199], v[68:71]
	v_mfma_f32_16x16x32_bf16 v[64:67], v[212:215], v[196:199], v[64:67]
	s_mov_b32 m0, s19
	s_add_u32 s82, s28, 0x80
	s_addc_u32 s83, s29, 0
	s_barrier
	ds_read_b128 v[168:171], v150 offset:16384
	ds_read_b128 v[172:175], v150 offset:17408
	ds_read_b128 v[176:179], v150 offset:18432
	ds_read_b128 v[180:183], v150 offset:19456
	ds_read_b128 v[184:187], v150 offset:20480
	ds_read_b128 v[188:191], v150 offset:21504
	ds_read_b128 v[192:195], v150 offset:22528
	ds_read_b128 v[196:199], v150 offset:23552
	global_load_lds_dwordx4 v134, s[28:29]
	s_mov_b32 m0, s42
	s_nop 0
	global_load_lds_dwordx4 v130, s[28:29]
	s_waitcnt vmcnt(10)
	s_barrier
	s_waitcnt lgkmcnt(0)
	s_waitcnt lgkmcnt(0)
	v_mfma_f32_16x16x32_bf16 v[60:63], v[152:155], v[168:171], 0
	v_mfma_f32_16x16x32_bf16 v[56:59], v[160:163], v[168:171], 0
	v_mfma_f32_16x16x32_bf16 v[44:47], v[152:155], v[176:179], 0
	v_mfma_f32_16x16x32_bf16 v[40:43], v[160:163], v[176:179], 0
	v_mfma_f32_16x16x32_bf16 v[28:31], v[152:155], v[184:187], 0
	v_mfma_f32_16x16x32_bf16 v[24:27], v[160:163], v[184:187], 0
	v_mfma_f32_16x16x32_bf16 v[12:15], v[152:155], v[192:195], 0
	v_mfma_f32_16x16x32_bf16 v[8:11], v[160:163], v[192:195], 0
	v_mfma_f32_16x16x32_bf16 v[60:63], v[156:159], v[172:175], v[60:63]
	v_mfma_f32_16x16x32_bf16 v[56:59], v[164:167], v[172:175], v[56:59]
	v_mfma_f32_16x16x32_bf16 v[44:47], v[156:159], v[180:183], v[44:47]
	v_mfma_f32_16x16x32_bf16 v[40:43], v[164:167], v[180:183], v[40:43]
	v_mfma_f32_16x16x32_bf16 v[28:31], v[156:159], v[188:191], v[28:31]
	v_mfma_f32_16x16x32_bf16 v[24:27], v[164:167], v[188:191], v[24:27]
	v_mfma_f32_16x16x32_bf16 v[12:15], v[156:159], v[196:199], v[12:15]
	v_mfma_f32_16x16x32_bf16 v[8:11], v[164:167], v[196:199], v[8:11]
	s_barrier
	v_add_u32_e32 v164, 0x18000, v145
	ds_read_b128 v[152:155], v164
	ds_read_b128 v[156:159], v164 offset:1024
	ds_read_b128 v[160:163], v164 offset:2048
	ds_read_b128 v[164:167], v164 offset:3072
	s_add_u32 s58, s26, 0x40000
	s_addc_u32 s59, s27, 0
	s_add_i32 s60, s48, s38
	s_mov_b32 m0, s60
	s_nop 0
	global_load_lds_dwordx4 v132, s[58:59]
	s_add_i32 m0, s60, 0x2000
	s_nop 0
	global_load_lds_dwordx4 v128, s[58:59]
	s_waitcnt vmcnt(8)
	s_barrier
	v_mfma_f32_16x16x32_bf16 v[52:55], v[200:203], v[168:171], 0
	v_mfma_f32_16x16x32_bf16 v[48:51], v[208:211], v[168:171], 0
	v_mfma_f32_16x16x32_bf16 v[36:39], v[200:203], v[176:179], 0
	v_mfma_f32_16x16x32_bf16 v[32:35], v[208:211], v[176:179], 0
	v_mfma_f32_16x16x32_bf16 v[20:23], v[200:203], v[184:187], 0
	v_mfma_f32_16x16x32_bf16 v[16:19], v[208:211], v[184:187], 0
	v_mfma_f32_16x16x32_bf16 v[4:7], v[200:203], v[192:195], 0
	v_mfma_f32_16x16x32_bf16 v[0:3], v[208:211], v[192:195], 0
	v_mfma_f32_16x16x32_bf16 v[52:55], v[204:207], v[172:175], v[52:55]
	v_mfma_f32_16x16x32_bf16 v[48:51], v[212:215], v[172:175], v[48:51]
	v_mfma_f32_16x16x32_bf16 v[36:39], v[204:207], v[180:183], v[36:39]
	v_mfma_f32_16x16x32_bf16 v[32:35], v[212:215], v[180:183], v[32:35]
	v_mfma_f32_16x16x32_bf16 v[20:23], v[204:207], v[188:191], v[20:23]
	v_mfma_f32_16x16x32_bf16 v[16:19], v[212:215], v[188:191], v[16:19]
	v_mfma_f32_16x16x32_bf16 v[4:7], v[204:207], v[196:199], v[4:7]
	v_mfma_f32_16x16x32_bf16 v[0:3], v[212:215], v[196:199], v[0:3]
	s_add_i32 s58, 0, 0x18000
	s_barrier
	s_branch .Lg131_mid
.LBB0_131:
	s_add_u32 s26, s20, 0xfffc0080
	s_addc_u32 s27, s21, -1
	s_cmp_eq_u32 s57, 12
	s_cselect_b32 s29, s13, s27
	s_cselect_b32 s28, s53, s26
	s_cselect_b32 s27, s11, s56
	s_cselect_b32 s26, s54, s55
	s_add_i32 m0, s19, 0xc000
	ds_read_b128 v[168:171], v150
	ds_read_b128 v[172:175], v150 offset:1024
	ds_read_b128 v[176:179], v150 offset:2048
	ds_read_b128 v[180:183], v150 offset:3072
	ds_read_b128 v[184:187], v150 offset:4096
	ds_read_b128 v[188:191], v150 offset:5120
	ds_read_b128 v[192:195], v150 offset:6144
	ds_read_b128 v[196:199], v150 offset:7168
	global_load_lds_dwordx4 v136, s[20:21]
	s_add_i32 m0, s19, 0xe000
	s_nop 0
	global_load_lds_dwordx4 v138, s[20:21]
	s_waitcnt lgkmcnt(8)
	s_barrier
	s_waitcnt lgkmcnt(0)
	s_waitcnt lgkmcnt(0)
	v_mfma_f32_16x16x32_bf16 v[124:127], v[152:155], v[168:171], v[124:127]
	v_mfma_f32_16x16x32_bf16 v[120:123], v[160:163], v[168:171], v[120:123]
	v_mfma_f32_16x16x32_bf16 v[108:111], v[152:155], v[176:179], v[108:111]
	v_mfma_f32_16x16x32_bf16 v[104:107], v[160:163], v[176:179], v[104:107]
	v_mfma_f32_16x16x32_bf16 v[92:95], v[152:155], v[184:187], v[92:95]
	v_mfma_f32_16x16x32_bf16 v[88:91], v[160:163], v[184:187], v[88:91]
	v_mfma_f32_16x16x32_bf16 v[76:79], v[152:155], v[192:195], v[76:79]
	v_mfma_f32_16x16x32_bf16 v[72:75], v[160:163], v[192:195], v[72:75]
	v_mfma_f32_16x16x32_bf16 v[124:127], v[156:159], v[172:175], v[124:127]
	v_mfma_f32_16x16x32_bf16 v[120:123], v[164:167], v[172:175], v[120:123]
	v_mfma_f32_16x16x32_bf16 v[108:111], v[156:159], v[180:183], v[108:111]
	v_mfma_f32_16x16x32_bf16 v[104:107], v[164:167], v[180:183], v[104:107]
	v_mfma_f32_16x16x32_bf16 v[92:95], v[156:159], v[188:191], v[92:95]
	v_mfma_f32_16x16x32_bf16 v[88:91], v[164:167], v[188:191], v[88:91]
	v_mfma_f32_16x16x32_bf16 v[76:79], v[156:159], v[196:199], v[76:79]
	v_mfma_f32_16x16x32_bf16 v[72:75], v[164:167], v[196:199], v[72:75]
	s_barrier
	s_add_i32 s58, s47, s38
	s_add_u32 s80, s26, 0x80
	s_addc_u32 s81, s27, 0
	s_mov_b32 m0, s58
	ds_read_b128 v[200:203], v151
	ds_read_b128 v[204:207], v151 offset:1024
	ds_read_b128 v[208:211], v151 offset:2048
	ds_read_b128 v[212:215], v151 offset:3072
	global_load_lds_dwordx4 v132, s[26:27]
	s_add_i32 m0, s58, 0x2000
	s_nop 0
	global_load_lds_dwordx4 v128, s[26:27]
	s_waitcnt vmcnt(10)
	s_barrier
	s_waitcnt lgkmcnt(0)
	s_waitcnt lgkmcnt(0)
	v_mfma_f32_16x16x32_bf16 v[116:119], v[200:203], v[168:171], v[116:119]
	v_mfma_f32_16x16x32_bf16 v[112:115], v[208:211], v[168:171], v[112:115]
	v_mfma_f32_16x16x32_bf16 v[100:103], v[200:203], v[176:179], v[100:103]
	v_mfma_f32_16x16x32_bf16 v[96:99], v[208:211], v[176:179], v[96:99]
	v_mfma_f32_16x16x32_bf16 v[84:87], v[200:203], v[184:187], v[84:87]
	v_mfma_f32_16x16x32_bf16 v[80:83], v[208:211], v[184:187], v[80:83]
	v_mfma_f32_16x16x32_bf16 v[68:71], v[200:203], v[192:195], v[68:71]
	v_mfma_f32_16x16x32_bf16 v[64:67], v[208:211], v[192:195], v[64:67]
	v_mfma_f32_16x16x32_bf16 v[116:119], v[204:207], v[172:175], v[116:119]
	v_mfma_f32_16x16x32_bf16 v[112:115], v[212:215], v[172:175], v[112:115]
	v_mfma_f32_16x16x32_bf16 v[100:103], v[204:207], v[180:183], v[100:103]
	v_mfma_f32_16x16x32_bf16 v[96:99], v[212:215], v[180:183], v[96:99]
	v_mfma_f32_16x16x32_bf16 v[84:87], v[204:207], v[188:191], v[84:87]
	v_mfma_f32_16x16x32_bf16 v[80:83], v[212:215], v[188:191], v[80:83]
	v_mfma_f32_16x16x32_bf16 v[68:71], v[204:207], v[196:199], v[68:71]
	v_mfma_f32_16x16x32_bf16 v[64:67], v[212:215], v[196:199], v[64:67]
	s_mov_b32 m0, s19
	s_add_u32 s82, s28, 0x80
	s_addc_u32 s83, s29, 0
	s_barrier
	ds_read_b128 v[168:171], v150 offset:16384
	ds_read_b128 v[172:175], v150 offset:17408
	ds_read_b128 v[176:179], v150 offset:18432
	ds_read_b128 v[180:183], v150 offset:19456
	ds_read_b128 v[184:187], v150 offset:20480
	ds_read_b128 v[188:191], v150 offset:21504
	ds_read_b128 v[192:195], v150 offset:22528
	ds_read_b128 v[196:199], v150 offset:23552
	global_load_lds_dwordx4 v134, s[28:29]
	s_mov_b32 m0, s42
	s_nop 0
	global_load_lds_dwordx4 v130, s[28:29]
	s_waitcnt vmcnt(10)
	s_barrier
	s_waitcnt lgkmcnt(0)
	s_waitcnt lgkmcnt(0)
	v_mfma_f32_16x16x32_bf16 v[60:63], v[152:155], v[168:171], v[60:63]
	v_mfma_f32_16x16x32_bf16 v[56:59], v[160:163], v[168:171], v[56:59]
	v_mfma_f32_16x16x32_bf16 v[44:47], v[152:155], v[176:179], v[44:47]
	v_mfma_f32_16x16x32_bf16 v[40:43], v[160:163], v[176:179], v[40:43]
	v_mfma_f32_16x16x32_bf16 v[28:31], v[152:155], v[184:187], v[28:31]
	v_mfma_f32_16x16x32_bf16 v[24:27], v[160:163], v[184:187], v[24:27]
	v_mfma_f32_16x16x32_bf16 v[12:15], v[152:155], v[192:195], v[12:15]
	v_mfma_f32_16x16x32_bf16 v[8:11], v[160:163], v[192:195], v[8:11]
	v_mfma_f32_16x16x32_bf16 v[60:63], v[156:159], v[172:175], v[60:63]
	v_mfma_f32_16x16x32_bf16 v[56:59], v[164:167], v[172:175], v[56:59]
	v_mfma_f32_16x16x32_bf16 v[44:47], v[156:159], v[180:183], v[44:47]
	v_mfma_f32_16x16x32_bf16 v[40:43], v[164:167], v[180:183], v[40:43]
	v_mfma_f32_16x16x32_bf16 v[28:31], v[156:159], v[188:191], v[28:31]
	v_mfma_f32_16x16x32_bf16 v[24:27], v[164:167], v[188:191], v[24:27]
	v_mfma_f32_16x16x32_bf16 v[12:15], v[156:159], v[196:199], v[12:15]
	v_mfma_f32_16x16x32_bf16 v[8:11], v[164:167], v[196:199], v[8:11]
	s_barrier
	v_add_u32_e32 v164, 0x18000, v145
	ds_read_b128 v[152:155], v164
	ds_read_b128 v[156:159], v164 offset:1024
	ds_read_b128 v[160:163], v164 offset:2048
	ds_read_b128 v[164:167], v164 offset:3072
	s_add_u32 s58, s26, 0x40000
	s_addc_u32 s59, s27, 0
	s_add_i32 s60, s48, s38
	s_mov_b32 m0, s60
	s_nop 0
	global_load_lds_dwordx4 v132, s[58:59]
	s_add_i32 m0, s60, 0x2000
	s_nop 0
	global_load_lds_dwordx4 v128, s[58:59]
	s_waitcnt vmcnt(8)
	s_barrier
	v_mfma_f32_16x16x32_bf16 v[52:55], v[200:203], v[168:171], v[52:55]
	v_mfma_f32_16x16x32_bf16 v[48:51], v[208:211], v[168:171], v[48:51]
	v_mfma_f32_16x16x32_bf16 v[36:39], v[200:203], v[176:179], v[36:39]
	v_mfma_f32_16x16x32_bf16 v[32:35], v[208:211], v[176:179], v[32:35]
	v_mfma_f32_16x16x32_bf16 v[20:23], v[200:203], v[184:187], v[20:23]
	v_mfma_f32_16x16x32_bf16 v[16:19], v[208:211], v[184:187], v[16:19]
	v_mfma_f32_16x16x32_bf16 v[4:7], v[200:203], v[192:195], v[4:7]
	v_mfma_f32_16x16x32_bf16 v[0:3], v[208:211], v[192:195], v[0:3]
	v_mfma_f32_16x16x32_bf16 v[52:55], v[204:207], v[172:175], v[52:55]
	v_mfma_f32_16x16x32_bf16 v[48:51], v[212:215], v[172:175], v[48:51]
	v_mfma_f32_16x16x32_bf16 v[36:39], v[204:207], v[180:183], v[36:39]
	v_mfma_f32_16x16x32_bf16 v[32:35], v[212:215], v[180:183], v[32:35]
	v_mfma_f32_16x16x32_bf16 v[20:23], v[204:207], v[188:191], v[20:23]
	v_mfma_f32_16x16x32_bf16 v[16:19], v[212:215], v[188:191], v[16:19]
	v_mfma_f32_16x16x32_bf16 v[4:7], v[204:207], v[196:199], v[4:7]
	v_mfma_f32_16x16x32_bf16 v[0:3], v[212:215], v[196:199], v[0:3]
	s_add_i32 s58, 0, 0x18000
	s_barrier
.Lg131_mid:
	s_add_u32 s28, s28, 0x40000
	s_addc_u32 s29, s29, 0
	s_mov_b32 m0, s43
	ds_read_b128 v[168:171], v150 offset:32768
	ds_read_b128 v[172:175], v150 offset:33792
	ds_read_b128 v[176:179], v150 offset:34816
	ds_read_b128 v[180:183], v150 offset:35840
	ds_read_b128 v[184:187], v150 offset:36864
	ds_read_b128 v[188:191], v150 offset:37888
	ds_read_b128 v[192:195], v150 offset:38912
	ds_read_b128 v[196:199], v150 offset:39936
	global_load_lds_dwordx4 v134, s[28:29]
	s_mov_b32 m0, s44
	s_nop 0
	global_load_lds_dwordx4 v130, s[28:29]
	s_waitcnt lgkmcnt(8)
	s_barrier
	s_waitcnt lgkmcnt(0)
	s_waitcnt lgkmcnt(0)
	v_mfma_f32_16x16x32_bf16 v[124:127], v[152:155], v[168:171], v[124:127]
	v_mfma_f32_16x16x32_bf16 v[120:123], v[160:163], v[168:171], v[120:123]
	v_mfma_f32_16x16x32_bf16 v[108:111], v[152:155], v[176:179], v[108:111]
	v_mfma_f32_16x16x32_bf16 v[104:107], v[160:163], v[176:179], v[104:107]
	v_mfma_f32_16x16x32_bf16 v[92:95], v[152:155], v[184:187], v[92:95]
	v_mfma_f32_16x16x32_bf16 v[88:91], v[160:163], v[184:187], v[88:91]
	v_mfma_f32_16x16x32_bf16 v[76:79], v[152:155], v[192:195], v[76:79]
	v_mfma_f32_16x16x32_bf16 v[72:75], v[160:163], v[192:195], v[72:75]
	v_mfma_f32_16x16x32_bf16 v[124:127], v[156:159], v[172:175], v[124:127]
	v_mfma_f32_16x16x32_bf16 v[120:123], v[164:167], v[172:175], v[120:123]
	v_mfma_f32_16x16x32_bf16 v[108:111], v[156:159], v[180:183], v[108:111]
	v_mfma_f32_16x16x32_bf16 v[104:107], v[164:167], v[180:183], v[104:107]
	v_mfma_f32_16x16x32_bf16 v[92:95], v[156:159], v[188:191], v[92:95]
	v_mfma_f32_16x16x32_bf16 v[88:91], v[164:167], v[188:191], v[88:91]
	v_mfma_f32_16x16x32_bf16 v[76:79], v[156:159], v[196:199], v[76:79]
	v_mfma_f32_16x16x32_bf16 v[72:75], v[164:167], v[196:199], v[72:75]
	s_barrier
	s_add_i32 s28, 0, 0x1c000
	s_add_i32 s29, s58, s38
	v_add_u32_e32 v212, s28, v145
	s_mov_b32 m0, s29
	ds_read_b128 v[200:203], v212
	ds_read_b128 v[204:207], v212 offset:1024
	ds_read_b128 v[208:211], v212 offset:2048
	ds_read_b128 v[212:215], v212 offset:3072
	global_load_lds_dwordx4 v132, s[80:81]
	s_add_i32 m0, s29, 0x2000
	s_nop 0
	global_load_lds_dwordx4 v128, s[80:81]
	s_waitcnt vmcnt(10)
	s_barrier
	s_waitcnt lgkmcnt(0)
	s_waitcnt lgkmcnt(0)
	v_mfma_f32_16x16x32_bf16 v[116:119], v[200:203], v[168:171], v[116:119]
	v_mfma_f32_16x16x32_bf16 v[112:115], v[208:211], v[168:171], v[112:115]
	v_mfma_f32_16x16x32_bf16 v[100:103], v[200:203], v[176:179], v[100:103]
	v_mfma_f32_16x16x32_bf16 v[96:99], v[208:211], v[176:179], v[96:99]
	v_mfma_f32_16x16x32_bf16 v[84:87], v[200:203], v[184:187], v[84:87]
	v_mfma_f32_16x16x32_bf16 v[80:83], v[208:211], v[184:187], v[80:83]
	v_mfma_f32_16x16x32_bf16 v[68:71], v[200:203], v[192:195], v[68:71]
	v_mfma_f32_16x16x32_bf16 v[64:67], v[208:211], v[192:195], v[64:67]
	v_mfma_f32_16x16x32_bf16 v[116:119], v[204:207], v[172:175], v[116:119]
	v_mfma_f32_16x16x32_bf16 v[112:115], v[212:215], v[172:175], v[112:115]
	v_mfma_f32_16x16x32_bf16 v[100:103], v[204:207], v[180:183], v[100:103]
	v_mfma_f32_16x16x32_bf16 v[96:99], v[212:215], v[180:183], v[96:99]
	v_mfma_f32_16x16x32_bf16 v[84:87], v[204:207], v[188:191], v[84:87]
	v_mfma_f32_16x16x32_bf16 v[80:83], v[212:215], v[188:191], v[80:83]
	v_mfma_f32_16x16x32_bf16 v[68:71], v[204:207], v[196:199], v[68:71]
	v_mfma_f32_16x16x32_bf16 v[64:67], v[212:215], v[196:199], v[64:67]
	s_mov_b32 m0, s45
	s_barrier
	ds_read_b128 v[168:171], v150 offset:49152
	ds_read_b128 v[172:175], v150 offset:50176
	ds_read_b128 v[176:179], v150 offset:51200
	ds_read_b128 v[180:183], v150 offset:52224
	ds_read_b128 v[184:187], v150 offset:53248
	ds_read_b128 v[188:191], v150 offset:54272
	ds_read_b128 v[192:195], v150 offset:55296
	ds_read_b128 v[196:199], v150 offset:56320
	global_load_lds_dwordx4 v134, s[82:83]
	s_mov_b32 m0, s46
	s_nop 0
	global_load_lds_dwordx4 v130, s[82:83]
	s_waitcnt vmcnt(10)
	s_barrier
	s_waitcnt lgkmcnt(0)
	s_waitcnt lgkmcnt(0)
	v_mfma_f32_16x16x32_bf16 v[60:63], v[152:155], v[168:171], v[60:63]
	v_mfma_f32_16x16x32_bf16 v[56:59], v[160:163], v[168:171], v[56:59]
	v_mfma_f32_16x16x32_bf16 v[44:47], v[152:155], v[176:179], v[44:47]
	v_mfma_f32_16x16x32_bf16 v[40:43], v[160:163], v[176:179], v[40:43]
	v_mfma_f32_16x16x32_bf16 v[28:31], v[152:155], v[184:187], v[28:31]
	v_mfma_f32_16x16x32_bf16 v[24:27], v[160:163], v[184:187], v[24:27]
	v_mfma_f32_16x16x32_bf16 v[12:15], v[152:155], v[192:195], v[12:15]
	v_mfma_f32_16x16x32_bf16 v[8:11], v[160:163], v[192:195], v[8:11]
	v_mfma_f32_16x16x32_bf16 v[60:63], v[156:159], v[172:175], v[60:63]
	v_mfma_f32_16x16x32_bf16 v[56:59], v[164:167], v[172:175], v[56:59]
	v_mfma_f32_16x16x32_bf16 v[44:47], v[156:159], v[180:183], v[44:47]
	v_mfma_f32_16x16x32_bf16 v[40:43], v[164:167], v[180:183], v[40:43]
	v_mfma_f32_16x16x32_bf16 v[28:31], v[156:159], v[188:191], v[28:31]
	v_mfma_f32_16x16x32_bf16 v[24:27], v[164:167], v[188:191], v[24:27]
	v_mfma_f32_16x16x32_bf16 v[12:15], v[156:159], v[196:199], v[12:15]
	v_mfma_f32_16x16x32_bf16 v[8:11], v[164:167], v[196:199], v[8:11]
	s_barrier
	ds_read_b128 v[152:155], v149
	ds_read_b128 v[156:159], v149 offset:1024
	ds_read_b128 v[160:163], v149 offset:2048
	ds_read_b128 v[164:167], v149 offset:3072
	s_add_u32 s26, s26, 0x40080
	s_addc_u32 s27, s27, 0
	s_add_i32 s28, s28, s38
	s_mov_b32 m0, s28
	s_nop 0
	global_load_lds_dwordx4 v132, s[26:27]
	s_add_i32 m0, s28, 0x2000
	s_nop 0
	global_load_lds_dwordx4 v128, s[26:27]
	s_waitcnt vmcnt(8)
	s_barrier
	v_mfma_f32_16x16x32_bf16 v[52:55], v[200:203], v[168:171], v[52:55]
	v_mfma_f32_16x16x32_bf16 v[48:51], v[208:211], v[168:171], v[48:51]
	v_mfma_f32_16x16x32_bf16 v[36:39], v[200:203], v[176:179], v[36:39]
	v_mfma_f32_16x16x32_bf16 v[32:35], v[208:211], v[176:179], v[32:35]
	v_mfma_f32_16x16x32_bf16 v[20:23], v[200:203], v[184:187], v[20:23]
	v_mfma_f32_16x16x32_bf16 v[16:19], v[208:211], v[184:187], v[16:19]
	v_mfma_f32_16x16x32_bf16 v[4:7], v[200:203], v[192:195], v[4:7]
	v_mfma_f32_16x16x32_bf16 v[0:3], v[208:211], v[192:195], v[0:3]
	v_mfma_f32_16x16x32_bf16 v[52:55], v[204:207], v[172:175], v[52:55]
	v_mfma_f32_16x16x32_bf16 v[48:51], v[212:215], v[172:175], v[48:51]
	v_mfma_f32_16x16x32_bf16 v[36:39], v[204:207], v[180:183], v[36:39]
	v_mfma_f32_16x16x32_bf16 v[32:35], v[212:215], v[180:183], v[32:35]
	v_mfma_f32_16x16x32_bf16 v[20:23], v[204:207], v[188:191], v[20:23]
	v_mfma_f32_16x16x32_bf16 v[16:19], v[212:215], v[188:191], v[16:19]
	v_mfma_f32_16x16x32_bf16 v[4:7], v[204:207], v[196:199], v[4:7]
	v_mfma_f32_16x16x32_bf16 v[0:3], v[212:215], v[196:199], v[0:3]
	s_add_i32 s57, s57, 2
	s_add_u32 s20, s20, 0x100
	s_addc_u32 s21, s21, 0
	s_add_u32 s55, s55, 0x100
	s_addc_u32 s56, s56, 0
	s_cmp_gt_u32 s57, 13
	s_barrier
	s_cbranch_scc0 .LBB0_131
	s_waitcnt lgkmcnt(0)
	s_setprio 0
	s_cmpk_gt_u32 s37, 0xff
	s_cbranch_scc1 .Lg131_nox
	s_barrier
	s_setprio 1

.Lg248_noy:
	ds_read_b128 v[144:147], v151
	ds_read_b128 v[156:159], v151 offset:1024
	ds_read_b128 v[160:163], v151 offset:2048
	ds_read_b128 v[164:167], v151 offset:3072
	s_add_u32 s26, s20, 0x100
	s_addc_u32 s27, s21, 0
	s_cmp_eq_u32 s59, 40
	s_cselect_b32 s31, s9, s27
	s_cselect_b32 s30, s8, s26
	s_cselect_b32 s29, s11, s58
	s_cselect_b32 s28, s10, s57
	s_add_i32 m0, s41, 0xc000
	ds_read_b128 v[168:171], v152
	ds_read_b128 v[172:175], v152 offset:1024
	ds_read_b128 v[176:179], v152 offset:2048
	ds_read_b128 v[180:183], v152 offset:3072
	ds_read_b128 v[184:187], v152 offset:4096
	ds_read_b128 v[188:191], v152 offset:5120
	ds_read_b128 v[192:195], v152 offset:6144
	ds_read_b128 v[196:199], v152 offset:7168
	global_load_lds_dwordx4 v136, s[20:21]
	s_add_i32 m0, s41, 0xe000
	s_nop 0
	global_load_lds_dwordx4 v138, s[20:21]
	s_waitcnt lgkmcnt(8)
	s_barrier
	s_waitcnt lgkmcnt(0)
	s_waitcnt lgkmcnt(0)
	v_mfma_f32_16x16x32_bf16 v[124:127], v[144:147], v[168:171], 0
	v_mfma_f32_16x16x32_bf16 v[120:123], v[160:163], v[168:171], 0
	v_mfma_f32_16x16x32_bf16 v[108:111], v[144:147], v[176:179], 0
	v_mfma_f32_16x16x32_bf16 v[104:107], v[160:163], v[176:179], 0
	v_mfma_f32_16x16x32_bf16 v[92:95], v[144:147], v[184:187], 0
	v_mfma_f32_16x16x32_bf16 v[88:91], v[160:163], v[184:187], 0
	v_mfma_f32_16x16x32_bf16 v[76:79], v[144:147], v[192:195], 0
	v_mfma_f32_16x16x32_bf16 v[72:75], v[160:163], v[192:195], 0
	v_mfma_f32_16x16x32_bf16 v[124:127], v[156:159], v[172:175], v[124:127]
	v_mfma_f32_16x16x32_bf16 v[120:123], v[164:167], v[172:175], v[120:123]
	v_mfma_f32_16x16x32_bf16 v[108:111], v[156:159], v[180:183], v[108:111]
	v_mfma_f32_16x16x32_bf16 v[104:107], v[164:167], v[180:183], v[104:107]
	v_mfma_f32_16x16x32_bf16 v[92:95], v[156:159], v[188:191], v[92:95]
	v_mfma_f32_16x16x32_bf16 v[88:91], v[164:167], v[188:191], v[88:91]
	v_mfma_f32_16x16x32_bf16 v[76:79], v[156:159], v[196:199], v[76:79]
	v_mfma_f32_16x16x32_bf16 v[72:75], v[164:167], v[196:199], v[72:75]
	s_barrier
	s_add_i32 s20, s51, s40
	s_add_u32 s80, s28, 0x80
	s_addc_u32 s81, s29, 0
	s_mov_b32 m0, s20
	ds_read_b128 v[200:203], v153
	ds_read_b128 v[204:207], v153 offset:1024
	ds_read_b128 v[208:211], v153 offset:2048
	ds_read_b128 v[212:215], v153 offset:3072
	global_load_lds_dwordx4 v130, s[28:29]
	s_add_i32 m0, s20, 0x2000
	s_nop 0
	global_load_lds_dwordx4 v134, s[28:29]
	s_waitcnt vmcnt(10)
	s_barrier
	s_waitcnt lgkmcnt(0)
	s_waitcnt lgkmcnt(0)
	v_mfma_f32_16x16x32_bf16 v[116:119], v[200:203], v[168:171], 0
	v_mfma_f32_16x16x32_bf16 v[112:115], v[208:211], v[168:171], 0
	v_mfma_f32_16x16x32_bf16 v[100:103], v[200:203], v[176:179], 0
	v_mfma_f32_16x16x32_bf16 v[96:99], v[208:211], v[176:179], 0
	v_mfma_f32_16x16x32_bf16 v[84:87], v[200:203], v[184:187], 0
	v_mfma_f32_16x16x32_bf16 v[80:83], v[208:211], v[184:187], 0
	v_mfma_f32_16x16x32_bf16 v[68:71], v[200:203], v[192:195], 0
	v_mfma_f32_16x16x32_bf16 v[64:67], v[208:211], v[192:195], 0
	v_mfma_f32_16x16x32_bf16 v[116:119], v[204:207], v[172:175], v[116:119]
	v_mfma_f32_16x16x32_bf16 v[112:115], v[212:215], v[172:175], v[112:115]
	v_mfma_f32_16x16x32_bf16 v[100:103], v[204:207], v[180:183], v[100:103]
	v_mfma_f32_16x16x32_bf16 v[96:99], v[212:215], v[180:183], v[96:99]
	v_mfma_f32_16x16x32_bf16 v[84:87], v[204:207], v[188:191], v[84:87]
	v_mfma_f32_16x16x32_bf16 v[80:83], v[212:215], v[188:191], v[80:83]
	v_mfma_f32_16x16x32_bf16 v[68:71], v[204:207], v[196:199], v[68:71]
	v_mfma_f32_16x16x32_bf16 v[64:67], v[212:215], v[196:199], v[64:67]
	s_mov_b32 m0, s41
	s_add_u32 s82, s30, 0x80
	s_addc_u32 s83, s31, 0
	s_barrier
	ds_read_b128 v[168:171], v152 offset:16384
	ds_read_b128 v[172:175], v152 offset:17408
	ds_read_b128 v[176:179], v152 offset:18432
	ds_read_b128 v[180:183], v152 offset:19456
	ds_read_b128 v[184:187], v152 offset:20480
	ds_read_b128 v[188:191], v152 offset:21504
	ds_read_b128 v[192:195], v152 offset:22528
	ds_read_b128 v[196:199], v152 offset:23552
	global_load_lds_dwordx4 v128, s[30:31]
	s_mov_b32 m0, s42
	s_nop 0
	global_load_lds_dwordx4 v132, s[30:31]
	s_waitcnt vmcnt(10)
	s_barrier
	s_waitcnt lgkmcnt(0)
	s_waitcnt lgkmcnt(0)
	v_mfma_f32_16x16x32_bf16 v[60:63], v[144:147], v[168:171], 0
	v_mfma_f32_16x16x32_bf16 v[56:59], v[160:163], v[168:171], 0
	v_mfma_f32_16x16x32_bf16 v[44:47], v[144:147], v[176:179], 0
	v_mfma_f32_16x16x32_bf16 v[40:43], v[160:163], v[176:179], 0
	v_mfma_f32_16x16x32_bf16 v[28:31], v[144:147], v[184:187], 0
	v_mfma_f32_16x16x32_bf16 v[24:27], v[160:163], v[184:187], 0
	v_mfma_f32_16x16x32_bf16 v[12:15], v[144:147], v[192:195], 0
	v_mfma_f32_16x16x32_bf16 v[8:11], v[160:163], v[192:195], 0
	v_mfma_f32_16x16x32_bf16 v[60:63], v[156:159], v[172:175], v[60:63]
	v_mfma_f32_16x16x32_bf16 v[56:59], v[164:167], v[172:175], v[56:59]
	v_mfma_f32_16x16x32_bf16 v[44:47], v[156:159], v[180:183], v[44:47]
	v_mfma_f32_16x16x32_bf16 v[40:43], v[164:167], v[180:183], v[40:43]
	v_mfma_f32_16x16x32_bf16 v[28:31], v[156:159], v[188:191], v[28:31]
	v_mfma_f32_16x16x32_bf16 v[24:27], v[164:167], v[188:191], v[24:27]
	v_mfma_f32_16x16x32_bf16 v[12:15], v[156:159], v[196:199], v[12:15]
	v_mfma_f32_16x16x32_bf16 v[8:11], v[164:167], v[196:199], v[8:11]
	s_barrier
	v_add_u32_e32 v155, 0x18000, v149
	ds_read_b128 v[144:147], v155
	ds_read_b128 v[156:159], v155 offset:1024
	ds_read_b128 v[160:163], v155 offset:2048
	ds_read_b128 v[164:167], v155 offset:3072
	s_add_u32 s20, s28, 0xb0000
	s_addc_u32 s21, s29, 0
	s_add_i32 s60, s52, s40
	s_mov_b32 m0, s60
	s_nop 0
	global_load_lds_dwordx4 v130, s[20:21]
	s_add_i32 m0, s60, 0x2000
	s_nop 0
	global_load_lds_dwordx4 v134, s[20:21]
	s_waitcnt vmcnt(8)
	s_barrier
	v_mfma_f32_16x16x32_bf16 v[52:55], v[200:203], v[168:171], 0
	v_mfma_f32_16x16x32_bf16 v[48:51], v[208:211], v[168:171], 0
	v_mfma_f32_16x16x32_bf16 v[36:39], v[200:203], v[176:179], 0
	v_mfma_f32_16x16x32_bf16 v[32:35], v[208:211], v[176:179], 0
	v_mfma_f32_16x16x32_bf16 v[20:23], v[200:203], v[184:187], 0
	v_mfma_f32_16x16x32_bf16 v[16:19], v[208:211], v[184:187], 0
	v_mfma_f32_16x16x32_bf16 v[4:7], v[200:203], v[192:195], 0
	v_mfma_f32_16x16x32_bf16 v[0:3], v[208:211], v[192:195], 0
	v_mfma_f32_16x16x32_bf16 v[52:55], v[204:207], v[172:175], v[52:55]
	v_mfma_f32_16x16x32_bf16 v[48:51], v[212:215], v[172:175], v[48:51]
	v_mfma_f32_16x16x32_bf16 v[36:39], v[204:207], v[180:183], v[36:39]
	v_mfma_f32_16x16x32_bf16 v[32:35], v[212:215], v[180:183], v[32:35]
	v_mfma_f32_16x16x32_bf16 v[20:23], v[204:207], v[188:191], v[20:23]
	v_mfma_f32_16x16x32_bf16 v[16:19], v[212:215], v[188:191], v[16:19]
	v_mfma_f32_16x16x32_bf16 v[4:7], v[204:207], v[196:199], v[4:7]
	v_mfma_f32_16x16x32_bf16 v[0:3], v[212:215], v[196:199], v[0:3]
	s_add_i32 s60, 0, 0x18000
	s_barrier
	s_branch .Lg248_mid
.LBB0_248:
	s_add_u32 s26, s20, 0x100
	s_addc_u32 s27, s21, 0
	s_cmp_eq_u32 s59, 40
	s_cselect_b32 s31, s9, s27
	s_cselect_b32 s30, s8, s26
	s_cselect_b32 s29, s11, s58
	s_cselect_b32 s28, s10, s57
	s_add_i32 m0, s41, 0xc000
	ds_read_b128 v[168:171], v152
	ds_read_b128 v[172:175], v152 offset:1024
	ds_read_b128 v[176:179], v152 offset:2048
	ds_read_b128 v[180:183], v152 offset:3072
	ds_read_b128 v[184:187], v152 offset:4096
	ds_read_b128 v[188:191], v152 offset:5120
	ds_read_b128 v[192:195], v152 offset:6144
	ds_read_b128 v[196:199], v152 offset:7168
	global_load_lds_dwordx4 v136, s[20:21]
	s_add_i32 m0, s41, 0xe000
	s_nop 0
	global_load_lds_dwordx4 v138, s[20:21]
	s_waitcnt lgkmcnt(8)
	s_barrier
	s_waitcnt lgkmcnt(0)
	s_waitcnt lgkmcnt(0)
	v_mfma_f32_16x16x32_bf16 v[124:127], v[144:147], v[168:171], v[124:127]
	v_mfma_f32_16x16x32_bf16 v[120:123], v[160:163], v[168:171], v[120:123]
	v_mfma_f32_16x16x32_bf16 v[108:111], v[144:147], v[176:179], v[108:111]
	v_mfma_f32_16x16x32_bf16 v[104:107], v[160:163], v[176:179], v[104:107]
	v_mfma_f32_16x16x32_bf16 v[92:95], v[144:147], v[184:187], v[92:95]
	v_mfma_f32_16x16x32_bf16 v[88:91], v[160:163], v[184:187], v[88:91]
	v_mfma_f32_16x16x32_bf16 v[76:79], v[144:147], v[192:195], v[76:79]
	v_mfma_f32_16x16x32_bf16 v[72:75], v[160:163], v[192:195], v[72:75]
	v_mfma_f32_16x16x32_bf16 v[124:127], v[156:159], v[172:175], v[124:127]
	v_mfma_f32_16x16x32_bf16 v[120:123], v[164:167], v[172:175], v[120:123]
	v_mfma_f32_16x16x32_bf16 v[108:111], v[156:159], v[180:183], v[108:111]
	v_mfma_f32_16x16x32_bf16 v[104:107], v[164:167], v[180:183], v[104:107]
	v_mfma_f32_16x16x32_bf16 v[92:95], v[156:159], v[188:191], v[92:95]
	v_mfma_f32_16x16x32_bf16 v[88:91], v[164:167], v[188:191], v[88:91]
	v_mfma_f32_16x16x32_bf16 v[76:79], v[156:159], v[196:199], v[76:79]
	v_mfma_f32_16x16x32_bf16 v[72:75], v[164:167], v[196:199], v[72:75]
	s_barrier
	s_add_i32 s20, s51, s40
	s_add_u32 s80, s28, 0x80
	s_addc_u32 s81, s29, 0
	s_mov_b32 m0, s20
	ds_read_b128 v[200:203], v153
	ds_read_b128 v[204:207], v153 offset:1024
	ds_read_b128 v[208:211], v153 offset:2048
	ds_read_b128 v[212:215], v153 offset:3072
	global_load_lds_dwordx4 v130, s[28:29]
	s_add_i32 m0, s20, 0x2000
	s_nop 0
	global_load_lds_dwordx4 v134, s[28:29]
	s_waitcnt vmcnt(10)
	s_barrier
	s_waitcnt lgkmcnt(0)
	s_waitcnt lgkmcnt(0)
	v_mfma_f32_16x16x32_bf16 v[116:119], v[200:203], v[168:171], v[116:119]
	v_mfma_f32_16x16x32_bf16 v[112:115], v[208:211], v[168:171], v[112:115]
	v_mfma_f32_16x16x32_bf16 v[100:103], v[200:203], v[176:179], v[100:103]
	v_mfma_f32_16x16x32_bf16 v[96:99], v[208:211], v[176:179], v[96:99]
	v_mfma_f32_16x16x32_bf16 v[84:87], v[200:203], v[184:187], v[84:87]
	v_mfma_f32_16x16x32_bf16 v[80:83], v[208:211], v[184:187], v[80:83]
	v_mfma_f32_16x16x32_bf16 v[68:71], v[200:203], v[192:195], v[68:71]
	v_mfma_f32_16x16x32_bf16 v[64:67], v[208:211], v[192:195], v[64:67]
	v_mfma_f32_16x16x32_bf16 v[116:119], v[204:207], v[172:175], v[116:119]
	v_mfma_f32_16x16x32_bf16 v[112:115], v[212:215], v[172:175], v[112:115]
	v_mfma_f32_16x16x32_bf16 v[100:103], v[204:207], v[180:183], v[100:103]
	v_mfma_f32_16x16x32_bf16 v[96:99], v[212:215], v[180:183], v[96:99]
	v_mfma_f32_16x16x32_bf16 v[84:87], v[204:207], v[188:191], v[84:87]
	v_mfma_f32_16x16x32_bf16 v[80:83], v[212:215], v[188:191], v[80:83]
	v_mfma_f32_16x16x32_bf16 v[68:71], v[204:207], v[196:199], v[68:71]
	v_mfma_f32_16x16x32_bf16 v[64:67], v[212:215], v[196:199], v[64:67]
	s_mov_b32 m0, s41
	s_add_u32 s82, s30, 0x80
	s_addc_u32 s83, s31, 0
	s_barrier
	ds_read_b128 v[168:171], v152 offset:16384
	ds_read_b128 v[172:175], v152 offset:17408
	ds_read_b128 v[176:179], v152 offset:18432
	ds_read_b128 v[180:183], v152 offset:19456
	ds_read_b128 v[184:187], v152 offset:20480
	ds_read_b128 v[188:191], v152 offset:21504
	ds_read_b128 v[192:195], v152 offset:22528
	ds_read_b128 v[196:199], v152 offset:23552
	global_load_lds_dwordx4 v128, s[30:31]
	s_mov_b32 m0, s42
	s_nop 0
	global_load_lds_dwordx4 v132, s[30:31]
	s_waitcnt vmcnt(10)
	s_barrier
	s_waitcnt lgkmcnt(0)
	s_waitcnt lgkmcnt(0)
	v_mfma_f32_16x16x32_bf16 v[60:63], v[144:147], v[168:171], v[60:63]
	v_mfma_f32_16x16x32_bf16 v[56:59], v[160:163], v[168:171], v[56:59]
	v_mfma_f32_16x16x32_bf16 v[44:47], v[144:147], v[176:179], v[44:47]
	v_mfma_f32_16x16x32_bf16 v[40:43], v[160:163], v[176:179], v[40:43]
	v_mfma_f32_16x16x32_bf16 v[28:31], v[144:147], v[184:187], v[28:31]
	v_mfma_f32_16x16x32_bf16 v[24:27], v[160:163], v[184:187], v[24:27]
	v_mfma_f32_16x16x32_bf16 v[12:15], v[144:147], v[192:195], v[12:15]
	v_mfma_f32_16x16x32_bf16 v[8:11], v[160:163], v[192:195], v[8:11]
	v_mfma_f32_16x16x32_bf16 v[60:63], v[156:159], v[172:175], v[60:63]
	v_mfma_f32_16x16x32_bf16 v[56:59], v[164:167], v[172:175], v[56:59]
	v_mfma_f32_16x16x32_bf16 v[44:47], v[156:159], v[180:183], v[44:47]
	v_mfma_f32_16x16x32_bf16 v[40:43], v[164:167], v[180:183], v[40:43]
	v_mfma_f32_16x16x32_bf16 v[28:31], v[156:159], v[188:191], v[28:31]
	v_mfma_f32_16x16x32_bf16 v[24:27], v[164:167], v[188:191], v[24:27]
	v_mfma_f32_16x16x32_bf16 v[12:15], v[156:159], v[196:199], v[12:15]
	v_mfma_f32_16x16x32_bf16 v[8:11], v[164:167], v[196:199], v[8:11]
	s_barrier
	v_add_u32_e32 v155, 0x18000, v149
	ds_read_b128 v[144:147], v155
	ds_read_b128 v[156:159], v155 offset:1024
	ds_read_b128 v[160:163], v155 offset:2048
	ds_read_b128 v[164:167], v155 offset:3072
	s_add_u32 s20, s28, 0xb0000
	s_addc_u32 s21, s29, 0
	s_add_i32 s60, s52, s40
	s_mov_b32 m0, s60
	s_nop 0
	global_load_lds_dwordx4 v130, s[20:21]
	s_add_i32 m0, s60, 0x2000
	s_nop 0
	global_load_lds_dwordx4 v134, s[20:21]
	s_waitcnt vmcnt(8)
	s_barrier
	v_mfma_f32_16x16x32_bf16 v[52:55], v[200:203], v[168:171], v[52:55]
	v_mfma_f32_16x16x32_bf16 v[48:51], v[208:211], v[168:171], v[48:51]
	v_mfma_f32_16x16x32_bf16 v[36:39], v[200:203], v[176:179], v[36:39]
	v_mfma_f32_16x16x32_bf16 v[32:35], v[208:211], v[176:179], v[32:35]
	v_mfma_f32_16x16x32_bf16 v[20:23], v[200:203], v[184:187], v[20:23]
	v_mfma_f32_16x16x32_bf16 v[16:19], v[208:211], v[184:187], v[16:19]
	v_mfma_f32_16x16x32_bf16 v[4:7], v[200:203], v[192:195], v[4:7]
	v_mfma_f32_16x16x32_bf16 v[0:3], v[208:211], v[192:195], v[0:3]
	v_mfma_f32_16x16x32_bf16 v[52:55], v[204:207], v[172:175], v[52:55]
	v_mfma_f32_16x16x32_bf16 v[48:51], v[212:215], v[172:175], v[48:51]
	v_mfma_f32_16x16x32_bf16 v[36:39], v[204:207], v[180:183], v[36:39]
	v_mfma_f32_16x16x32_bf16 v[32:35], v[212:215], v[180:183], v[32:35]
	v_mfma_f32_16x16x32_bf16 v[20:23], v[204:207], v[188:191], v[20:23]
	v_mfma_f32_16x16x32_bf16 v[16:19], v[212:215], v[188:191], v[16:19]
	v_mfma_f32_16x16x32_bf16 v[4:7], v[204:207], v[196:199], v[4:7]
	v_mfma_f32_16x16x32_bf16 v[0:3], v[212:215], v[196:199], v[0:3]
	s_add_i32 s60, 0, 0x18000
	s_barrier
.Lg248_mid:
	s_add_u32 s20, s30, 0xb0000
	s_addc_u32 s21, s31, 0
	s_mov_b32 m0, s43
	ds_read_b128 v[168:171], v152 offset:32768
	ds_read_b128 v[172:175], v152 offset:33792
	ds_read_b128 v[176:179], v152 offset:34816
	ds_read_b128 v[180:183], v152 offset:35840
	ds_read_b128 v[184:187], v152 offset:36864
	ds_read_b128 v[188:191], v152 offset:37888
	ds_read_b128 v[192:195], v152 offset:38912
	ds_read_b128 v[196:199], v152 offset:39936
	global_load_lds_dwordx4 v128, s[20:21]
	s_mov_b32 m0, s44
	s_nop 0
	global_load_lds_dwordx4 v132, s[20:21]
	s_waitcnt lgkmcnt(8)
	s_barrier
	s_waitcnt lgkmcnt(0)
	s_waitcnt lgkmcnt(0)
	v_mfma_f32_16x16x32_bf16 v[124:127], v[144:147], v[168:171], v[124:127]
	v_mfma_f32_16x16x32_bf16 v[120:123], v[160:163], v[168:171], v[120:123]
	v_mfma_f32_16x16x32_bf16 v[108:111], v[144:147], v[176:179], v[108:111]
	v_mfma_f32_16x16x32_bf16 v[104:107], v[160:163], v[176:179], v[104:107]
	v_mfma_f32_16x16x32_bf16 v[92:95], v[144:147], v[184:187], v[92:95]
	v_mfma_f32_16x16x32_bf16 v[88:91], v[160:163], v[184:187], v[88:91]
	v_mfma_f32_16x16x32_bf16 v[76:79], v[144:147], v[192:195], v[76:79]
	v_mfma_f32_16x16x32_bf16 v[72:75], v[160:163], v[192:195], v[72:75]
	v_mfma_f32_16x16x32_bf16 v[124:127], v[156:159], v[172:175], v[124:127]
	v_mfma_f32_16x16x32_bf16 v[120:123], v[164:167], v[172:175], v[120:123]
	v_mfma_f32_16x16x32_bf16 v[108:111], v[156:159], v[180:183], v[108:111]
	v_mfma_f32_16x16x32_bf16 v[104:107], v[164:167], v[180:183], v[104:107]
	v_mfma_f32_16x16x32_bf16 v[92:95], v[156:159], v[188:191], v[92:95]
	v_mfma_f32_16x16x32_bf16 v[88:91], v[164:167], v[188:191], v[88:91]
	v_mfma_f32_16x16x32_bf16 v[76:79], v[156:159], v[196:199], v[76:79]
	v_mfma_f32_16x16x32_bf16 v[72:75], v[164:167], v[196:199], v[72:75]
	s_barrier
	s_add_i32 s30, 0, 0x1c000
	s_add_i32 s20, s60, s40
	v_add_u32_e32 v155, s30, v149
	s_mov_b32 m0, s20
	ds_read_b128 v[200:203], v155
	ds_read_b128 v[204:207], v155 offset:1024
	ds_read_b128 v[208:211], v155 offset:2048
	ds_read_b128 v[212:215], v155 offset:3072
	global_load_lds_dwordx4 v130, s[80:81]
	s_add_i32 m0, s20, 0x2000
	s_nop 0
	global_load_lds_dwordx4 v134, s[80:81]
	s_waitcnt vmcnt(10)
	s_barrier
	s_waitcnt lgkmcnt(0)
	s_waitcnt lgkmcnt(0)
	v_mfma_f32_16x16x32_bf16 v[116:119], v[200:203], v[168:171], v[116:119]
	v_mfma_f32_16x16x32_bf16 v[112:115], v[208:211], v[168:171], v[112:115]
	v_mfma_f32_16x16x32_bf16 v[100:103], v[200:203], v[176:179], v[100:103]
	v_mfma_f32_16x16x32_bf16 v[96:99], v[208:211], v[176:179], v[96:99]
	v_mfma_f32_16x16x32_bf16 v[84:87], v[200:203], v[184:187], v[84:87]
	v_mfma_f32_16x16x32_bf16 v[80:83], v[208:211], v[184:187], v[80:83]
	v_mfma_f32_16x16x32_bf16 v[68:71], v[200:203], v[192:195], v[68:71]
	v_mfma_f32_16x16x32_bf16 v[64:67], v[208:211], v[192:195], v[64:67]
	v_mfma_f32_16x16x32_bf16 v[116:119], v[204:207], v[172:175], v[116:119]
	v_mfma_f32_16x16x32_bf16 v[112:115], v[212:215], v[172:175], v[112:115]
	v_mfma_f32_16x16x32_bf16 v[100:103], v[204:207], v[180:183], v[100:103]
	v_mfma_f32_16x16x32_bf16 v[96:99], v[212:215], v[180:183], v[96:99]
	v_mfma_f32_16x16x32_bf16 v[84:87], v[204:207], v[188:191], v[84:87]
	v_mfma_f32_16x16x32_bf16 v[80:83], v[212:215], v[188:191], v[80:83]
	v_mfma_f32_16x16x32_bf16 v[68:71], v[204:207], v[196:199], v[68:71]
	v_mfma_f32_16x16x32_bf16 v[64:67], v[212:215], v[196:199], v[64:67]
	s_mov_b32 m0, s46
	s_barrier
	ds_read_b128 v[168:171], v152 offset:49152
	ds_read_b128 v[172:175], v152 offset:50176
	ds_read_b128 v[176:179], v152 offset:51200
	ds_read_b128 v[180:183], v152 offset:52224
	ds_read_b128 v[184:187], v152 offset:53248
	ds_read_b128 v[188:191], v152 offset:54272
	ds_read_b128 v[192:195], v152 offset:55296
	ds_read_b128 v[196:199], v152 offset:56320
	global_load_lds_dwordx4 v128, s[82:83]
	s_mov_b32 m0, s47
	s_nop 0
	global_load_lds_dwordx4 v132, s[82:83]
	s_waitcnt vmcnt(10)
	s_barrier
	s_waitcnt lgkmcnt(0)
	s_waitcnt lgkmcnt(0)
	v_mfma_f32_16x16x32_bf16 v[60:63], v[144:147], v[168:171], v[60:63]
	v_mfma_f32_16x16x32_bf16 v[56:59], v[160:163], v[168:171], v[56:59]
	v_mfma_f32_16x16x32_bf16 v[44:47], v[144:147], v[176:179], v[44:47]
	v_mfma_f32_16x16x32_bf16 v[40:43], v[160:163], v[176:179], v[40:43]
	v_mfma_f32_16x16x32_bf16 v[28:31], v[144:147], v[184:187], v[28:31]
	v_mfma_f32_16x16x32_bf16 v[24:27], v[160:163], v[184:187], v[24:27]
	v_mfma_f32_16x16x32_bf16 v[12:15], v[144:147], v[192:195], v[12:15]
	v_mfma_f32_16x16x32_bf16 v[8:11], v[160:163], v[192:195], v[8:11]
	v_mfma_f32_16x16x32_bf16 v[60:63], v[156:159], v[172:175], v[60:63]
	v_mfma_f32_16x16x32_bf16 v[56:59], v[164:167], v[172:175], v[56:59]
	v_mfma_f32_16x16x32_bf16 v[44:47], v[156:159], v[180:183], v[44:47]
	v_mfma_f32_16x16x32_bf16 v[40:43], v[164:167], v[180:183], v[40:43]
	v_mfma_f32_16x16x32_bf16 v[28:31], v[156:159], v[188:191], v[28:31]
	v_mfma_f32_16x16x32_bf16 v[24:27], v[164:167], v[188:191], v[24:27]
	v_mfma_f32_16x16x32_bf16 v[12:15], v[156:159], v[196:199], v[12:15]
	v_mfma_f32_16x16x32_bf16 v[8:11], v[164:167], v[196:199], v[8:11]
	s_barrier
	ds_read_b128 v[144:147], v151
	ds_read_b128 v[156:159], v151 offset:1024
	ds_read_b128 v[160:163], v151 offset:2048
	ds_read_b128 v[164:167], v151 offset:3072
	s_add_u32 s20, s28, 0xb0080
	s_addc_u32 s21, s29, 0
	s_add_i32 s28, s30, s40
	s_mov_b32 m0, s28
	s_nop 0
	global_load_lds_dwordx4 v130, s[20:21]
	s_add_i32 m0, s28, 0x2000
	s_nop 0
	global_load_lds_dwordx4 v134, s[20:21]
	s_waitcnt vmcnt(8)
	s_barrier
	v_mfma_f32_16x16x32_bf16 v[52:55], v[200:203], v[168:171], v[52:55]
	v_mfma_f32_16x16x32_bf16 v[48:51], v[208:211], v[168:171], v[48:51]
	v_mfma_f32_16x16x32_bf16 v[36:39], v[200:203], v[176:179], v[36:39]
	v_mfma_f32_16x16x32_bf16 v[32:35], v[208:211], v[176:179], v[32:35]
	v_mfma_f32_16x16x32_bf16 v[20:23], v[200:203], v[184:187], v[20:23]
	v_mfma_f32_16x16x32_bf16 v[16:19], v[208:211], v[184:187], v[16:19]
	v_mfma_f32_16x16x32_bf16 v[4:7], v[200:203], v[192:195], v[4:7]
	v_mfma_f32_16x16x32_bf16 v[0:3], v[208:211], v[192:195], v[0:3]
	v_mfma_f32_16x16x32_bf16 v[52:55], v[204:207], v[172:175], v[52:55]
	v_mfma_f32_16x16x32_bf16 v[48:51], v[212:215], v[172:175], v[48:51]
	v_mfma_f32_16x16x32_bf16 v[36:39], v[204:207], v[180:183], v[36:39]
	v_mfma_f32_16x16x32_bf16 v[32:35], v[212:215], v[180:183], v[32:35]
	v_mfma_f32_16x16x32_bf16 v[20:23], v[204:207], v[188:191], v[20:23]
	v_mfma_f32_16x16x32_bf16 v[16:19], v[212:215], v[188:191], v[16:19]
	v_mfma_f32_16x16x32_bf16 v[4:7], v[204:207], v[196:199], v[4:7]
	v_mfma_f32_16x16x32_bf16 v[0:3], v[212:215], v[196:199], v[0:3]
	s_add_i32 s59, s59, 2
	s_add_u32 s57, s57, 0x100
	s_addc_u32 s58, s58, 0
	s_cmp_gt_u32 s59, 41
	s_mov_b64 s[20:21], s[26:27]
	s_barrier
	s_cbranch_scc0 .LBB0_248
	s_waitcnt lgkmcnt(0)
	s_setprio 0
	v_lshl_add_u32 v146, s56, 8, v148
	v_ashrrev_i32_e32 v147, 31, v146
	v_lshl_or_b32 v144, s12, 8, v150
	v_lshlrev_b64 v[156:157], 11, v[146:147]
	v_ashrrev_i32_e32 v145, 31, v144
	v_lshl_add_u64 v[156:157], s[14:15], 0, v[156:157]
	v_lshl_add_u64 v[166:167], v[144:145], 1, v[156:157]
	global_load_dwordx4 v[158:161], v[166:167], off
	global_load_dwordx4 v[162:165], v[166:167], off offset:256
	s_mov_b64 s[84:85], 0x8000
	s_mov_b64 s[86:87], 0x28000
	v_lshl_add_u64 v[232:233], v[166:167], 0, s[84:85]
	global_load_dwordx4 v[176:179], v[232:233], off
	global_load_dwordx4 v[180:183], v[232:233], off offset:256
	v_lshl_add_u64 v[232:233], v[232:233], 0, s[84:85]
	global_load_dwordx4 v[184:187], v[232:233], off
	global_load_dwordx4 v[188:191], v[232:233], off offset:256
	v_lshl_add_u64 v[232:233], v[232:233], 0, s[84:85]
	global_load_dwordx4 v[192:195], v[232:233], off
	global_load_dwordx4 v[196:199], v[232:233], off offset:256
	v_lshl_add_u64 v[232:233], v[232:233], 0, s[86:87]
	global_load_dwordx4 v[200:203], v[232:233], off
	global_load_dwordx4 v[204:207], v[232:233], off offset:256
	v_lshl_add_u64 v[232:233], v[232:233], 0, s[84:85]
	global_load_dwordx4 v[208:211], v[232:233], off
	global_load_dwordx4 v[212:215], v[232:233], off offset:256
	v_lshl_add_u64 v[232:233], v[232:233], 0, s[84:85]
	global_load_dwordx4 v[216:219], v[232:233], off
	global_load_dwordx4 v[220:223], v[232:233], off offset:256
	v_lshl_add_u64 v[232:233], v[232:233], 0, s[84:85]
	global_load_dwordx4 v[224:227], v[232:233], off
	global_load_dwordx4 v[228:231], v[232:233], off offset:256
	s_cmpk_gt_u32 s35, 0xff
	s_cbranch_scc1 .Lg248_nox
	s_barrier
	s_setprio 1

.Lg359_noy:
	ds_read_b128 v[128:131], v181
	ds_read_b128 v[132:135], v181 offset:1024
	ds_read_b128 v[136:139], v181 offset:2048
	ds_read_b128 v[166:169], v181 offset:3072
	s_add_u32 s38, s8, 0xfffc0080
	s_addc_u32 s39, s9, -1
	s_cmp_eq_u32 s75, 12
	s_cselect_b32 s41, s21, s39
	s_cselect_b32 s40, s71, s38
	s_cselect_b32 s39, s19, s74
	s_cselect_b32 s38, s72, s73
	s_add_i32 m0, s37, 0xc000
	ds_read_b128 v[170:173], v182
	ds_read_b128 v[174:177], v182 offset:1024
	ds_read_b128 v[192:195], v182 offset:2048
	ds_read_b128 v[196:199], v182 offset:3072
	ds_read_b128 v[200:203], v182 offset:4096
	ds_read_b128 v[204:207], v182 offset:5120
	ds_read_b128 v[208:211], v182 offset:6144
	ds_read_b128 v[212:215], v182 offset:7168
	global_load_lds_dwordx4 v158, s[8:9]
	s_add_i32 m0, s37, 0xe000
	s_nop 0
	global_load_lds_dwordx4 v160, s[8:9]
	s_waitcnt lgkmcnt(8)
	s_barrier
	s_waitcnt lgkmcnt(0)
	s_waitcnt lgkmcnt(0)
	v_mfma_f32_16x16x32_bf16 v[124:127], v[128:131], v[170:173], 0
	v_mfma_f32_16x16x32_bf16 v[116:119], v[136:139], v[170:173], 0
	v_mfma_f32_16x16x32_bf16 v[108:111], v[128:131], v[192:195], 0
	v_mfma_f32_16x16x32_bf16 v[100:103], v[136:139], v[192:195], 0
	v_mfma_f32_16x16x32_bf16 v[92:95], v[128:131], v[200:203], 0
	v_mfma_f32_16x16x32_bf16 v[84:87], v[136:139], v[200:203], 0
	v_mfma_f32_16x16x32_bf16 v[76:79], v[128:131], v[208:211], 0
	v_mfma_f32_16x16x32_bf16 v[68:71], v[136:139], v[208:211], 0
	v_mfma_f32_16x16x32_bf16 v[124:127], v[132:135], v[174:177], v[124:127]
	v_mfma_f32_16x16x32_bf16 v[116:119], v[166:169], v[174:177], v[116:119]
	v_mfma_f32_16x16x32_bf16 v[108:111], v[132:135], v[196:199], v[108:111]
	v_mfma_f32_16x16x32_bf16 v[100:103], v[166:169], v[196:199], v[100:103]
	v_mfma_f32_16x16x32_bf16 v[92:95], v[132:135], v[204:207], v[92:95]
	v_mfma_f32_16x16x32_bf16 v[84:87], v[166:169], v[204:207], v[84:87]
	v_mfma_f32_16x16x32_bf16 v[76:79], v[132:135], v[212:215], v[76:79]
	v_mfma_f32_16x16x32_bf16 v[68:71], v[166:169], v[212:215], v[68:71]
	s_barrier
	s_add_i32 s76, s63, s46
	s_add_u32 s80, s38, 0x80
	s_addc_u32 s81, s39, 0
	s_mov_b32 m0, s76
	ds_read_b128 v[216:219], v183
	ds_read_b128 v[220:223], v183 offset:1024
	ds_read_b128 v[224:227], v183 offset:2048
	ds_read_b128 v[228:231], v183 offset:3072
	global_load_lds_dwordx4 v144, s[38:39]
	s_add_i32 m0, s76, 0x2000
	s_nop 0
	global_load_lds_dwordx4 v148, s[38:39]
	s_waitcnt vmcnt(10)
	s_barrier
	s_waitcnt lgkmcnt(0)
	s_waitcnt lgkmcnt(0)
	v_mfma_f32_16x16x32_bf16 v[120:123], v[216:219], v[170:173], 0
	v_mfma_f32_16x16x32_bf16 v[112:115], v[224:227], v[170:173], 0
	v_mfma_f32_16x16x32_bf16 v[104:107], v[216:219], v[192:195], 0
	v_mfma_f32_16x16x32_bf16 v[96:99], v[224:227], v[192:195], 0
	v_mfma_f32_16x16x32_bf16 v[88:91], v[216:219], v[200:203], 0
	v_mfma_f32_16x16x32_bf16 v[80:83], v[224:227], v[200:203], 0
	v_mfma_f32_16x16x32_bf16 v[72:75], v[216:219], v[208:211], 0
	v_mfma_f32_16x16x32_bf16 v[64:67], v[224:227], v[208:211], 0
	v_mfma_f32_16x16x32_bf16 v[120:123], v[220:223], v[174:177], v[120:123]
	v_mfma_f32_16x16x32_bf16 v[112:115], v[228:231], v[174:177], v[112:115]
	v_mfma_f32_16x16x32_bf16 v[104:107], v[220:223], v[196:199], v[104:107]
	v_mfma_f32_16x16x32_bf16 v[96:99], v[228:231], v[196:199], v[96:99]
	v_mfma_f32_16x16x32_bf16 v[88:91], v[220:223], v[204:207], v[88:91]
	v_mfma_f32_16x16x32_bf16 v[80:83], v[228:231], v[204:207], v[80:83]
	v_mfma_f32_16x16x32_bf16 v[72:75], v[220:223], v[212:215], v[72:75]
	v_mfma_f32_16x16x32_bf16 v[64:67], v[228:231], v[212:215], v[64:67]
	s_mov_b32 m0, s37
	s_add_u32 s82, s40, 0x80
	s_addc_u32 s83, s41, 0
	s_barrier
	ds_read_b128 v[170:173], v182 offset:16384
	ds_read_b128 v[174:177], v182 offset:17408
	ds_read_b128 v[192:195], v182 offset:18432
	ds_read_b128 v[196:199], v182 offset:19456
	ds_read_b128 v[200:203], v182 offset:20480
	ds_read_b128 v[204:207], v182 offset:21504
	ds_read_b128 v[208:211], v182 offset:22528
	ds_read_b128 v[212:215], v182 offset:23552
	global_load_lds_dwordx4 v142, s[40:41]
	s_mov_b32 m0, s51
	s_nop 0
	global_load_lds_dwordx4 v146, s[40:41]
	s_waitcnt vmcnt(10)
	s_barrier
	s_waitcnt lgkmcnt(0)
	s_waitcnt lgkmcnt(0)
	v_mfma_f32_16x16x32_bf16 v[60:63], v[128:131], v[170:173], 0
	v_mfma_f32_16x16x32_bf16 v[52:55], v[136:139], v[170:173], 0
	v_mfma_f32_16x16x32_bf16 v[44:47], v[128:131], v[192:195], 0
	v_mfma_f32_16x16x32_bf16 v[36:39], v[136:139], v[192:195], 0
	v_mfma_f32_16x16x32_bf16 v[28:31], v[128:131], v[200:203], 0
	v_mfma_f32_16x16x32_bf16 v[20:23], v[136:139], v[200:203], 0
	v_mfma_f32_16x16x32_bf16 v[12:15], v[128:131], v[208:211], 0
	v_mfma_f32_16x16x32_bf16 v[4:7], v[136:139], v[208:211], 0
	v_mfma_f32_16x16x32_bf16 v[60:63], v[132:135], v[174:177], v[60:63]
	v_mfma_f32_16x16x32_bf16 v[52:55], v[166:169], v[174:177], v[52:55]
	v_mfma_f32_16x16x32_bf16 v[44:47], v[132:135], v[196:199], v[44:47]
	v_mfma_f32_16x16x32_bf16 v[36:39], v[166:169], v[196:199], v[36:39]
	v_mfma_f32_16x16x32_bf16 v[28:31], v[132:135], v[204:207], v[28:31]
	v_mfma_f32_16x16x32_bf16 v[20:23], v[166:169], v[204:207], v[20:23]
	v_mfma_f32_16x16x32_bf16 v[12:15], v[132:135], v[212:215], v[12:15]
	v_mfma_f32_16x16x32_bf16 v[4:7], v[166:169], v[212:215], v[4:7]
	s_barrier
	v_add_u32_e32 v150, 0x18000, v179
	ds_read_b128 v[128:131], v150
	ds_read_b128 v[132:135], v150 offset:1024
	ds_read_b128 v[136:139], v150 offset:2048
	ds_read_b128 v[166:169], v150 offset:3072
	s_add_u32 s76, s38, 0x40000
	s_addc_u32 s77, s39, 0
	s_add_i32 s78, s64, s46
	s_mov_b32 m0, s78
	s_nop 0
	global_load_lds_dwordx4 v144, s[76:77]
	s_add_i32 m0, s78, 0x2000
	s_nop 0
	global_load_lds_dwordx4 v148, s[76:77]
	s_waitcnt vmcnt(8)
	s_barrier
	v_mfma_f32_16x16x32_bf16 v[56:59], v[216:219], v[170:173], 0
	v_mfma_f32_16x16x32_bf16 v[48:51], v[224:227], v[170:173], 0
	v_mfma_f32_16x16x32_bf16 v[40:43], v[216:219], v[192:195], 0
	v_mfma_f32_16x16x32_bf16 v[32:35], v[224:227], v[192:195], 0
	v_mfma_f32_16x16x32_bf16 v[24:27], v[216:219], v[200:203], 0
	v_mfma_f32_16x16x32_bf16 v[16:19], v[224:227], v[200:203], 0
	v_mfma_f32_16x16x32_bf16 v[8:11], v[216:219], v[208:211], 0
	v_mfma_f32_16x16x32_bf16 v[0:3], v[224:227], v[208:211], 0
	v_mfma_f32_16x16x32_bf16 v[56:59], v[220:223], v[174:177], v[56:59]
	v_mfma_f32_16x16x32_bf16 v[48:51], v[228:231], v[174:177], v[48:51]
	v_mfma_f32_16x16x32_bf16 v[40:43], v[220:223], v[196:199], v[40:43]
	v_mfma_f32_16x16x32_bf16 v[32:35], v[228:231], v[196:199], v[32:35]
	v_mfma_f32_16x16x32_bf16 v[24:27], v[220:223], v[204:207], v[24:27]
	v_mfma_f32_16x16x32_bf16 v[16:19], v[228:231], v[204:207], v[16:19]
	v_mfma_f32_16x16x32_bf16 v[8:11], v[220:223], v[212:215], v[8:11]
	v_mfma_f32_16x16x32_bf16 v[0:3], v[228:231], v[212:215], v[0:3]
	s_add_i32 s76, 0, 0x18000
	s_barrier
	s_branch .Lg359_mid
.LBB0_359:
	s_add_u32 s38, s8, 0xfffc0080
	s_addc_u32 s39, s9, -1
	s_cmp_eq_u32 s75, 12
	s_cselect_b32 s41, s21, s39
	s_cselect_b32 s40, s71, s38
	s_cselect_b32 s39, s19, s74
	s_cselect_b32 s38, s72, s73
	s_add_i32 m0, s37, 0xc000
	ds_read_b128 v[170:173], v182
	ds_read_b128 v[174:177], v182 offset:1024
	ds_read_b128 v[192:195], v182 offset:2048
	ds_read_b128 v[196:199], v182 offset:3072
	ds_read_b128 v[200:203], v182 offset:4096
	ds_read_b128 v[204:207], v182 offset:5120
	ds_read_b128 v[208:211], v182 offset:6144
	ds_read_b128 v[212:215], v182 offset:7168
	global_load_lds_dwordx4 v158, s[8:9]
	s_add_i32 m0, s37, 0xe000
	s_nop 0
	global_load_lds_dwordx4 v160, s[8:9]
	s_waitcnt lgkmcnt(8)
	s_barrier
	s_waitcnt lgkmcnt(0)
	s_waitcnt lgkmcnt(0)
	v_mfma_f32_16x16x32_bf16 v[124:127], v[128:131], v[170:173], v[124:127]
	v_mfma_f32_16x16x32_bf16 v[116:119], v[136:139], v[170:173], v[116:119]
	v_mfma_f32_16x16x32_bf16 v[108:111], v[128:131], v[192:195], v[108:111]
	v_mfma_f32_16x16x32_bf16 v[100:103], v[136:139], v[192:195], v[100:103]
	v_mfma_f32_16x16x32_bf16 v[92:95], v[128:131], v[200:203], v[92:95]
	v_mfma_f32_16x16x32_bf16 v[84:87], v[136:139], v[200:203], v[84:87]
	v_mfma_f32_16x16x32_bf16 v[76:79], v[128:131], v[208:211], v[76:79]
	v_mfma_f32_16x16x32_bf16 v[68:71], v[136:139], v[208:211], v[68:71]
	v_mfma_f32_16x16x32_bf16 v[124:127], v[132:135], v[174:177], v[124:127]
	v_mfma_f32_16x16x32_bf16 v[116:119], v[166:169], v[174:177], v[116:119]
	v_mfma_f32_16x16x32_bf16 v[108:111], v[132:135], v[196:199], v[108:111]
	v_mfma_f32_16x16x32_bf16 v[100:103], v[166:169], v[196:199], v[100:103]
	v_mfma_f32_16x16x32_bf16 v[92:95], v[132:135], v[204:207], v[92:95]
	v_mfma_f32_16x16x32_bf16 v[84:87], v[166:169], v[204:207], v[84:87]
	v_mfma_f32_16x16x32_bf16 v[76:79], v[132:135], v[212:215], v[76:79]
	v_mfma_f32_16x16x32_bf16 v[68:71], v[166:169], v[212:215], v[68:71]
	s_barrier
	s_add_i32 s76, s63, s46
	s_add_u32 s80, s38, 0x80
	s_addc_u32 s81, s39, 0
	s_mov_b32 m0, s76
	ds_read_b128 v[216:219], v183
	ds_read_b128 v[220:223], v183 offset:1024
	ds_read_b128 v[224:227], v183 offset:2048
	ds_read_b128 v[228:231], v183 offset:3072
	global_load_lds_dwordx4 v144, s[38:39]
	s_add_i32 m0, s76, 0x2000
	s_nop 0
	global_load_lds_dwordx4 v148, s[38:39]
	s_waitcnt vmcnt(10)
	s_barrier
	s_waitcnt lgkmcnt(0)
	s_waitcnt lgkmcnt(0)
	v_mfma_f32_16x16x32_bf16 v[120:123], v[216:219], v[170:173], v[120:123]
	v_mfma_f32_16x16x32_bf16 v[112:115], v[224:227], v[170:173], v[112:115]
	v_mfma_f32_16x16x32_bf16 v[104:107], v[216:219], v[192:195], v[104:107]
	v_mfma_f32_16x16x32_bf16 v[96:99], v[224:227], v[192:195], v[96:99]
	v_mfma_f32_16x16x32_bf16 v[88:91], v[216:219], v[200:203], v[88:91]
	v_mfma_f32_16x16x32_bf16 v[80:83], v[224:227], v[200:203], v[80:83]
	v_mfma_f32_16x16x32_bf16 v[72:75], v[216:219], v[208:211], v[72:75]
	v_mfma_f32_16x16x32_bf16 v[64:67], v[224:227], v[208:211], v[64:67]
	v_mfma_f32_16x16x32_bf16 v[120:123], v[220:223], v[174:177], v[120:123]
	v_mfma_f32_16x16x32_bf16 v[112:115], v[228:231], v[174:177], v[112:115]
	v_mfma_f32_16x16x32_bf16 v[104:107], v[220:223], v[196:199], v[104:107]
	v_mfma_f32_16x16x32_bf16 v[96:99], v[228:231], v[196:199], v[96:99]
	v_mfma_f32_16x16x32_bf16 v[88:91], v[220:223], v[204:207], v[88:91]
	v_mfma_f32_16x16x32_bf16 v[80:83], v[228:231], v[204:207], v[80:83]
	v_mfma_f32_16x16x32_bf16 v[72:75], v[220:223], v[212:215], v[72:75]
	v_mfma_f32_16x16x32_bf16 v[64:67], v[228:231], v[212:215], v[64:67]
	s_mov_b32 m0, s37
	s_add_u32 s82, s40, 0x80
	s_addc_u32 s83, s41, 0
	s_barrier
	ds_read_b128 v[170:173], v182 offset:16384
	ds_read_b128 v[174:177], v182 offset:17408
	ds_read_b128 v[192:195], v182 offset:18432
	ds_read_b128 v[196:199], v182 offset:19456
	ds_read_b128 v[200:203], v182 offset:20480
	ds_read_b128 v[204:207], v182 offset:21504
	ds_read_b128 v[208:211], v182 offset:22528
	ds_read_b128 v[212:215], v182 offset:23552
	global_load_lds_dwordx4 v142, s[40:41]
	s_mov_b32 m0, s51
	s_nop 0
	global_load_lds_dwordx4 v146, s[40:41]
	s_waitcnt vmcnt(10)
	s_barrier
	s_waitcnt lgkmcnt(0)
	s_waitcnt lgkmcnt(0)
	v_mfma_f32_16x16x32_bf16 v[60:63], v[128:131], v[170:173], v[60:63]
	v_mfma_f32_16x16x32_bf16 v[52:55], v[136:139], v[170:173], v[52:55]
	v_mfma_f32_16x16x32_bf16 v[44:47], v[128:131], v[192:195], v[44:47]
	v_mfma_f32_16x16x32_bf16 v[36:39], v[136:139], v[192:195], v[36:39]
	v_mfma_f32_16x16x32_bf16 v[28:31], v[128:131], v[200:203], v[28:31]
	v_mfma_f32_16x16x32_bf16 v[20:23], v[136:139], v[200:203], v[20:23]
	v_mfma_f32_16x16x32_bf16 v[12:15], v[128:131], v[208:211], v[12:15]
	v_mfma_f32_16x16x32_bf16 v[4:7], v[136:139], v[208:211], v[4:7]
	v_mfma_f32_16x16x32_bf16 v[60:63], v[132:135], v[174:177], v[60:63]
	v_mfma_f32_16x16x32_bf16 v[52:55], v[166:169], v[174:177], v[52:55]
	v_mfma_f32_16x16x32_bf16 v[44:47], v[132:135], v[196:199], v[44:47]
	v_mfma_f32_16x16x32_bf16 v[36:39], v[166:169], v[196:199], v[36:39]
	v_mfma_f32_16x16x32_bf16 v[28:31], v[132:135], v[204:207], v[28:31]
	v_mfma_f32_16x16x32_bf16 v[20:23], v[166:169], v[204:207], v[20:23]
	v_mfma_f32_16x16x32_bf16 v[12:15], v[132:135], v[212:215], v[12:15]
	v_mfma_f32_16x16x32_bf16 v[4:7], v[166:169], v[212:215], v[4:7]
	s_barrier
	v_add_u32_e32 v150, 0x18000, v179
	ds_read_b128 v[128:131], v150
	ds_read_b128 v[132:135], v150 offset:1024
	ds_read_b128 v[136:139], v150 offset:2048
	ds_read_b128 v[166:169], v150 offset:3072
	s_add_u32 s76, s38, 0x40000
	s_addc_u32 s77, s39, 0
	s_add_i32 s78, s64, s46
	s_mov_b32 m0, s78
	s_nop 0
	global_load_lds_dwordx4 v144, s[76:77]
	s_add_i32 m0, s78, 0x2000
	s_nop 0
	global_load_lds_dwordx4 v148, s[76:77]
	s_waitcnt vmcnt(8)
	s_barrier
	v_mfma_f32_16x16x32_bf16 v[56:59], v[216:219], v[170:173], v[56:59]
	v_mfma_f32_16x16x32_bf16 v[48:51], v[224:227], v[170:173], v[48:51]
	v_mfma_f32_16x16x32_bf16 v[40:43], v[216:219], v[192:195], v[40:43]
	v_mfma_f32_16x16x32_bf16 v[32:35], v[224:227], v[192:195], v[32:35]
	v_mfma_f32_16x16x32_bf16 v[24:27], v[216:219], v[200:203], v[24:27]
	v_mfma_f32_16x16x32_bf16 v[16:19], v[224:227], v[200:203], v[16:19]
	v_mfma_f32_16x16x32_bf16 v[8:11], v[216:219], v[208:211], v[8:11]
	v_mfma_f32_16x16x32_bf16 v[0:3], v[224:227], v[208:211], v[0:3]
	v_mfma_f32_16x16x32_bf16 v[56:59], v[220:223], v[174:177], v[56:59]
	v_mfma_f32_16x16x32_bf16 v[48:51], v[228:231], v[174:177], v[48:51]
	v_mfma_f32_16x16x32_bf16 v[40:43], v[220:223], v[196:199], v[40:43]
	v_mfma_f32_16x16x32_bf16 v[32:35], v[228:231], v[196:199], v[32:35]
	v_mfma_f32_16x16x32_bf16 v[24:27], v[220:223], v[204:207], v[24:27]
	v_mfma_f32_16x16x32_bf16 v[16:19], v[228:231], v[204:207], v[16:19]
	v_mfma_f32_16x16x32_bf16 v[8:11], v[220:223], v[212:215], v[8:11]
	v_mfma_f32_16x16x32_bf16 v[0:3], v[228:231], v[212:215], v[0:3]
	s_add_i32 s76, 0, 0x18000
	s_barrier
.Lg359_mid:
	s_add_u32 s40, s40, 0x40000
	s_addc_u32 s41, s41, 0
	s_mov_b32 m0, s52
	ds_read_b128 v[170:173], v182 offset:32768
	ds_read_b128 v[174:177], v182 offset:33792
	ds_read_b128 v[192:195], v182 offset:34816
	ds_read_b128 v[196:199], v182 offset:35840
	ds_read_b128 v[200:203], v182 offset:36864
	ds_read_b128 v[204:207], v182 offset:37888
	ds_read_b128 v[208:211], v182 offset:38912
	ds_read_b128 v[212:215], v182 offset:39936
	global_load_lds_dwordx4 v142, s[40:41]
	s_mov_b32 m0, s53
	s_nop 0
	global_load_lds_dwordx4 v146, s[40:41]
	s_waitcnt lgkmcnt(8)
	s_barrier
	s_waitcnt lgkmcnt(0)
	s_waitcnt lgkmcnt(0)
	v_mfma_f32_16x16x32_bf16 v[124:127], v[128:131], v[170:173], v[124:127]
	v_mfma_f32_16x16x32_bf16 v[116:119], v[136:139], v[170:173], v[116:119]
	v_mfma_f32_16x16x32_bf16 v[108:111], v[128:131], v[192:195], v[108:111]
	v_mfma_f32_16x16x32_bf16 v[100:103], v[136:139], v[192:195], v[100:103]
	v_mfma_f32_16x16x32_bf16 v[92:95], v[128:131], v[200:203], v[92:95]
	v_mfma_f32_16x16x32_bf16 v[84:87], v[136:139], v[200:203], v[84:87]
	v_mfma_f32_16x16x32_bf16 v[76:79], v[128:131], v[208:211], v[76:79]
	v_mfma_f32_16x16x32_bf16 v[68:71], v[136:139], v[208:211], v[68:71]
	v_mfma_f32_16x16x32_bf16 v[124:127], v[132:135], v[174:177], v[124:127]
	v_mfma_f32_16x16x32_bf16 v[116:119], v[166:169], v[174:177], v[116:119]
	v_mfma_f32_16x16x32_bf16 v[108:111], v[132:135], v[196:199], v[108:111]
	v_mfma_f32_16x16x32_bf16 v[100:103], v[166:169], v[196:199], v[100:103]
	v_mfma_f32_16x16x32_bf16 v[92:95], v[132:135], v[204:207], v[92:95]
	v_mfma_f32_16x16x32_bf16 v[84:87], v[166:169], v[204:207], v[84:87]
	v_mfma_f32_16x16x32_bf16 v[76:79], v[132:135], v[212:215], v[76:79]
	v_mfma_f32_16x16x32_bf16 v[68:71], v[166:169], v[212:215], v[68:71]
	s_barrier
	s_add_i32 s40, 0, 0x1c000
	s_add_i32 s41, s76, s46
	v_add_u32_e32 v150, s40, v179
	s_mov_b32 m0, s41
	ds_read_b128 v[216:219], v150
	ds_read_b128 v[220:223], v150 offset:1024
	ds_read_b128 v[224:227], v150 offset:2048
	ds_read_b128 v[228:231], v150 offset:3072
	global_load_lds_dwordx4 v144, s[80:81]
	s_add_i32 m0, s41, 0x2000
	s_nop 0
	global_load_lds_dwordx4 v148, s[80:81]
	s_waitcnt vmcnt(10)
	s_barrier
	s_waitcnt lgkmcnt(0)
	s_waitcnt lgkmcnt(0)
	v_mfma_f32_16x16x32_bf16 v[120:123], v[216:219], v[170:173], v[120:123]
	v_mfma_f32_16x16x32_bf16 v[112:115], v[224:227], v[170:173], v[112:115]
	v_mfma_f32_16x16x32_bf16 v[104:107], v[216:219], v[192:195], v[104:107]
	v_mfma_f32_16x16x32_bf16 v[96:99], v[224:227], v[192:195], v[96:99]
	v_mfma_f32_16x16x32_bf16 v[88:91], v[216:219], v[200:203], v[88:91]
	v_mfma_f32_16x16x32_bf16 v[80:83], v[224:227], v[200:203], v[80:83]
	v_mfma_f32_16x16x32_bf16 v[72:75], v[216:219], v[208:211], v[72:75]
	v_mfma_f32_16x16x32_bf16 v[64:67], v[224:227], v[208:211], v[64:67]
	v_mfma_f32_16x16x32_bf16 v[120:123], v[220:223], v[174:177], v[120:123]
	v_mfma_f32_16x16x32_bf16 v[112:115], v[228:231], v[174:177], v[112:115]
	v_mfma_f32_16x16x32_bf16 v[104:107], v[220:223], v[196:199], v[104:107]
	v_mfma_f32_16x16x32_bf16 v[96:99], v[228:231], v[196:199], v[96:99]
	v_mfma_f32_16x16x32_bf16 v[88:91], v[220:223], v[204:207], v[88:91]
	v_mfma_f32_16x16x32_bf16 v[80:83], v[228:231], v[204:207], v[80:83]
	v_mfma_f32_16x16x32_bf16 v[72:75], v[220:223], v[212:215], v[72:75]
	v_mfma_f32_16x16x32_bf16 v[64:67], v[228:231], v[212:215], v[64:67]
	s_mov_b32 m0, s55
	s_barrier
	ds_read_b128 v[170:173], v182 offset:49152
	ds_read_b128 v[174:177], v182 offset:50176
	ds_read_b128 v[192:195], v182 offset:51200
	ds_read_b128 v[196:199], v182 offset:52224
	ds_read_b128 v[200:203], v182 offset:53248
	ds_read_b128 v[204:207], v182 offset:54272
	ds_read_b128 v[208:211], v182 offset:55296
	ds_read_b128 v[212:215], v182 offset:56320
	global_load_lds_dwordx4 v142, s[82:83]
	s_mov_b32 m0, s56
	s_nop 0
	global_load_lds_dwordx4 v146, s[82:83]
	s_waitcnt vmcnt(10)
	s_barrier
	s_waitcnt lgkmcnt(0)
	s_waitcnt lgkmcnt(0)
	v_mfma_f32_16x16x32_bf16 v[60:63], v[128:131], v[170:173], v[60:63]
	v_mfma_f32_16x16x32_bf16 v[52:55], v[136:139], v[170:173], v[52:55]
	v_mfma_f32_16x16x32_bf16 v[44:47], v[128:131], v[192:195], v[44:47]
	v_mfma_f32_16x16x32_bf16 v[36:39], v[136:139], v[192:195], v[36:39]
	v_mfma_f32_16x16x32_bf16 v[28:31], v[128:131], v[200:203], v[28:31]
	v_mfma_f32_16x16x32_bf16 v[20:23], v[136:139], v[200:203], v[20:23]
	v_mfma_f32_16x16x32_bf16 v[12:15], v[128:131], v[208:211], v[12:15]
	v_mfma_f32_16x16x32_bf16 v[4:7], v[136:139], v[208:211], v[4:7]
	v_mfma_f32_16x16x32_bf16 v[60:63], v[132:135], v[174:177], v[60:63]
	v_mfma_f32_16x16x32_bf16 v[52:55], v[166:169], v[174:177], v[52:55]
	v_mfma_f32_16x16x32_bf16 v[44:47], v[132:135], v[196:199], v[44:47]
	v_mfma_f32_16x16x32_bf16 v[36:39], v[166:169], v[196:199], v[36:39]
	v_mfma_f32_16x16x32_bf16 v[28:31], v[132:135], v[204:207], v[28:31]
	v_mfma_f32_16x16x32_bf16 v[20:23], v[166:169], v[204:207], v[20:23]
	v_mfma_f32_16x16x32_bf16 v[12:15], v[132:135], v[212:215], v[12:15]
	v_mfma_f32_16x16x32_bf16 v[4:7], v[166:169], v[212:215], v[4:7]
	s_barrier
	ds_read_b128 v[128:131], v181
	ds_read_b128 v[132:135], v181 offset:1024
	ds_read_b128 v[136:139], v181 offset:2048
	ds_read_b128 v[166:169], v181 offset:3072
	s_add_u32 s38, s38, 0x40080
	s_addc_u32 s39, s39, 0
	s_add_i32 s40, s40, s46
	s_mov_b32 m0, s40
	s_nop 0
	global_load_lds_dwordx4 v144, s[38:39]
	s_add_i32 m0, s40, 0x2000
	s_nop 0
	global_load_lds_dwordx4 v148, s[38:39]
	s_waitcnt vmcnt(8)
	s_barrier
	v_mfma_f32_16x16x32_bf16 v[56:59], v[216:219], v[170:173], v[56:59]
	v_mfma_f32_16x16x32_bf16 v[48:51], v[224:227], v[170:173], v[48:51]
	v_mfma_f32_16x16x32_bf16 v[40:43], v[216:219], v[192:195], v[40:43]
	v_mfma_f32_16x16x32_bf16 v[32:35], v[224:227], v[192:195], v[32:35]
	v_mfma_f32_16x16x32_bf16 v[24:27], v[216:219], v[200:203], v[24:27]
	v_mfma_f32_16x16x32_bf16 v[16:19], v[224:227], v[200:203], v[16:19]
	v_mfma_f32_16x16x32_bf16 v[8:11], v[216:219], v[208:211], v[8:11]
	v_mfma_f32_16x16x32_bf16 v[0:3], v[224:227], v[208:211], v[0:3]
	v_mfma_f32_16x16x32_bf16 v[56:59], v[220:223], v[174:177], v[56:59]
	v_mfma_f32_16x16x32_bf16 v[48:51], v[228:231], v[174:177], v[48:51]
	v_mfma_f32_16x16x32_bf16 v[40:43], v[220:223], v[196:199], v[40:43]
	v_mfma_f32_16x16x32_bf16 v[32:35], v[228:231], v[196:199], v[32:35]
	v_mfma_f32_16x16x32_bf16 v[24:27], v[220:223], v[204:207], v[24:27]
	v_mfma_f32_16x16x32_bf16 v[16:19], v[228:231], v[204:207], v[16:19]
	v_mfma_f32_16x16x32_bf16 v[8:11], v[220:223], v[212:215], v[8:11]
	v_mfma_f32_16x16x32_bf16 v[0:3], v[228:231], v[212:215], v[0:3]
	s_add_i32 s75, s75, 2
	s_add_u32 s8, s8, 0x100
	s_addc_u32 s9, s9, 0
	s_add_u32 s73, s73, 0x100
	s_addc_u32 s74, s74, 0
	s_cmp_gt_u32 s75, 13
	s_barrier
	s_cbranch_scc0 .LBB0_359
	s_waitcnt lgkmcnt(0)
	s_setprio 0
	s_cmpk_gt_u32 s45, 0xff
	s_cbranch_scc1 .Lg359_nox
	s_barrier
	s_setprio 1

.Lg786_noy:
	ds_read_b128 v[144:147], v151
	ds_read_b128 v[156:159], v151 offset:1024
	ds_read_b128 v[160:163], v151 offset:2048
	ds_read_b128 v[164:167], v151 offset:3072
	s_add_u32 s30, s28, 0xfffc0080
	s_addc_u32 s31, s29, -1
	s_cmp_eq_u32 s61, 12
	s_cselect_b32 s35, s19, s31
	s_cselect_b32 s34, s57, s30
	s_cselect_b32 s31, s17, s60
	s_cselect_b32 s30, s58, s59
	s_add_i32 m0, s45, 0xc000
	ds_read_b128 v[168:171], v152
	ds_read_b128 v[172:175], v152 offset:1024
	ds_read_b128 v[176:179], v152 offset:2048
	ds_read_b128 v[180:183], v152 offset:3072
	ds_read_b128 v[184:187], v152 offset:4096
	ds_read_b128 v[188:191], v152 offset:5120
	ds_read_b128 v[192:195], v152 offset:6144
	ds_read_b128 v[196:199], v152 offset:7168
	global_load_lds_dwordx4 v136, s[28:29]
	s_add_i32 m0, s45, 0xe000
	s_nop 0
	global_load_lds_dwordx4 v138, s[28:29]
	s_waitcnt lgkmcnt(8)
	s_barrier
	s_waitcnt lgkmcnt(0)
	s_waitcnt lgkmcnt(0)
	v_mfma_f32_16x16x32_bf16 v[124:127], v[144:147], v[168:171], 0
	v_mfma_f32_16x16x32_bf16 v[120:123], v[160:163], v[168:171], 0
	v_mfma_f32_16x16x32_bf16 v[108:111], v[144:147], v[176:179], 0
	v_mfma_f32_16x16x32_bf16 v[104:107], v[160:163], v[176:179], 0
	v_mfma_f32_16x16x32_bf16 v[92:95], v[144:147], v[184:187], 0
	v_mfma_f32_16x16x32_bf16 v[88:91], v[160:163], v[184:187], 0
	v_mfma_f32_16x16x32_bf16 v[76:79], v[144:147], v[192:195], 0
	v_mfma_f32_16x16x32_bf16 v[72:75], v[160:163], v[192:195], 0
	v_mfma_f32_16x16x32_bf16 v[124:127], v[156:159], v[172:175], v[124:127]
	v_mfma_f32_16x16x32_bf16 v[120:123], v[164:167], v[172:175], v[120:123]
	v_mfma_f32_16x16x32_bf16 v[108:111], v[156:159], v[180:183], v[108:111]
	v_mfma_f32_16x16x32_bf16 v[104:107], v[164:167], v[180:183], v[104:107]
	v_mfma_f32_16x16x32_bf16 v[92:95], v[156:159], v[188:191], v[92:95]
	v_mfma_f32_16x16x32_bf16 v[88:91], v[164:167], v[188:191], v[88:91]
	v_mfma_f32_16x16x32_bf16 v[76:79], v[156:159], v[196:199], v[76:79]
	v_mfma_f32_16x16x32_bf16 v[72:75], v[164:167], v[196:199], v[72:75]
	s_barrier
	s_add_i32 s62, s53, s42
	s_add_u32 s80, s30, 0x80
	s_addc_u32 s81, s31, 0
	s_mov_b32 m0, s62
	ds_read_b128 v[200:203], v153
	ds_read_b128 v[204:207], v153 offset:1024
	ds_read_b128 v[208:211], v153 offset:2048
	ds_read_b128 v[212:215], v153 offset:3072
	global_load_lds_dwordx4 v132, s[30:31]
	s_add_i32 m0, s62, 0x2000
	s_nop 0
	global_load_lds_dwordx4 v128, s[30:31]
	s_waitcnt vmcnt(10)
	s_barrier
	s_waitcnt lgkmcnt(0)
	s_waitcnt lgkmcnt(0)
	v_mfma_f32_16x16x32_bf16 v[116:119], v[200:203], v[168:171], 0
	v_mfma_f32_16x16x32_bf16 v[112:115], v[208:211], v[168:171], 0
	v_mfma_f32_16x16x32_bf16 v[100:103], v[200:203], v[176:179], 0
	v_mfma_f32_16x16x32_bf16 v[96:99], v[208:211], v[176:179], 0
	v_mfma_f32_16x16x32_bf16 v[84:87], v[200:203], v[184:187], 0
	v_mfma_f32_16x16x32_bf16 v[80:83], v[208:211], v[184:187], 0
	v_mfma_f32_16x16x32_bf16 v[68:71], v[200:203], v[192:195], 0
	v_mfma_f32_16x16x32_bf16 v[64:67], v[208:211], v[192:195], 0
	v_mfma_f32_16x16x32_bf16 v[116:119], v[204:207], v[172:175], v[116:119]
	v_mfma_f32_16x16x32_bf16 v[112:115], v[212:215], v[172:175], v[112:115]
	v_mfma_f32_16x16x32_bf16 v[100:103], v[204:207], v[180:183], v[100:103]
	v_mfma_f32_16x16x32_bf16 v[96:99], v[212:215], v[180:183], v[96:99]
	v_mfma_f32_16x16x32_bf16 v[84:87], v[204:207], v[188:191], v[84:87]
	v_mfma_f32_16x16x32_bf16 v[80:83], v[212:215], v[188:191], v[80:83]
	v_mfma_f32_16x16x32_bf16 v[68:71], v[204:207], v[196:199], v[68:71]
	v_mfma_f32_16x16x32_bf16 v[64:67], v[212:215], v[196:199], v[64:67]
	s_mov_b32 m0, s45
	s_add_u32 s82, s34, 0x80
	s_addc_u32 s83, s35, 0
	s_barrier
	ds_read_b128 v[168:171], v152 offset:16384
	ds_read_b128 v[172:175], v152 offset:17408
	ds_read_b128 v[176:179], v152 offset:18432
	ds_read_b128 v[180:183], v152 offset:19456
	ds_read_b128 v[184:187], v152 offset:20480
	ds_read_b128 v[188:191], v152 offset:21504
	ds_read_b128 v[192:195], v152 offset:22528
	ds_read_b128 v[196:199], v152 offset:23552
	global_load_lds_dwordx4 v134, s[34:35]
	s_mov_b32 m0, s46
	s_nop 0
	global_load_lds_dwordx4 v130, s[34:35]
	s_waitcnt vmcnt(10)
	s_barrier
	s_waitcnt lgkmcnt(0)
	s_waitcnt lgkmcnt(0)
	v_mfma_f32_16x16x32_bf16 v[60:63], v[144:147], v[168:171], 0
	v_mfma_f32_16x16x32_bf16 v[56:59], v[160:163], v[168:171], 0
	v_mfma_f32_16x16x32_bf16 v[44:47], v[144:147], v[176:179], 0
	v_mfma_f32_16x16x32_bf16 v[40:43], v[160:163], v[176:179], 0
	v_mfma_f32_16x16x32_bf16 v[28:31], v[144:147], v[184:187], 0
	v_mfma_f32_16x16x32_bf16 v[24:27], v[160:163], v[184:187], 0
	v_mfma_f32_16x16x32_bf16 v[12:15], v[144:147], v[192:195], 0
	v_mfma_f32_16x16x32_bf16 v[8:11], v[160:163], v[192:195], 0
	v_mfma_f32_16x16x32_bf16 v[60:63], v[156:159], v[172:175], v[60:63]
	v_mfma_f32_16x16x32_bf16 v[56:59], v[164:167], v[172:175], v[56:59]
	v_mfma_f32_16x16x32_bf16 v[44:47], v[156:159], v[180:183], v[44:47]
	v_mfma_f32_16x16x32_bf16 v[40:43], v[164:167], v[180:183], v[40:43]
	v_mfma_f32_16x16x32_bf16 v[28:31], v[156:159], v[188:191], v[28:31]
	v_mfma_f32_16x16x32_bf16 v[24:27], v[164:167], v[188:191], v[24:27]
	v_mfma_f32_16x16x32_bf16 v[12:15], v[156:159], v[196:199], v[12:15]
	v_mfma_f32_16x16x32_bf16 v[8:11], v[164:167], v[196:199], v[8:11]
	s_barrier
	v_add_u32_e32 v155, 0x18000, v149
	ds_read_b128 v[144:147], v155
	ds_read_b128 v[156:159], v155 offset:1024
	ds_read_b128 v[160:163], v155 offset:2048
	ds_read_b128 v[164:167], v155 offset:3072
	s_add_u32 s62, s30, 0x40000
	s_addc_u32 s63, s31, 0
	s_add_i32 s64, s54, s42
	s_mov_b32 m0, s64
	s_nop 0
	global_load_lds_dwordx4 v132, s[62:63]
	s_add_i32 m0, s64, 0x2000
	s_nop 0
	global_load_lds_dwordx4 v128, s[62:63]
	s_waitcnt vmcnt(8)
	s_barrier
	v_mfma_f32_16x16x32_bf16 v[52:55], v[200:203], v[168:171], 0
	v_mfma_f32_16x16x32_bf16 v[48:51], v[208:211], v[168:171], 0
	v_mfma_f32_16x16x32_bf16 v[36:39], v[200:203], v[176:179], 0
	v_mfma_f32_16x16x32_bf16 v[32:35], v[208:211], v[176:179], 0
	v_mfma_f32_16x16x32_bf16 v[20:23], v[200:203], v[184:187], 0
	v_mfma_f32_16x16x32_bf16 v[16:19], v[208:211], v[184:187], 0
	v_mfma_f32_16x16x32_bf16 v[4:7], v[200:203], v[192:195], 0
	v_mfma_f32_16x16x32_bf16 v[0:3], v[208:211], v[192:195], 0
	v_mfma_f32_16x16x32_bf16 v[52:55], v[204:207], v[172:175], v[52:55]
	v_mfma_f32_16x16x32_bf16 v[48:51], v[212:215], v[172:175], v[48:51]
	v_mfma_f32_16x16x32_bf16 v[36:39], v[204:207], v[180:183], v[36:39]
	v_mfma_f32_16x16x32_bf16 v[32:35], v[212:215], v[180:183], v[32:35]
	v_mfma_f32_16x16x32_bf16 v[20:23], v[204:207], v[188:191], v[20:23]
	v_mfma_f32_16x16x32_bf16 v[16:19], v[212:215], v[188:191], v[16:19]
	v_mfma_f32_16x16x32_bf16 v[4:7], v[204:207], v[196:199], v[4:7]
	v_mfma_f32_16x16x32_bf16 v[0:3], v[212:215], v[196:199], v[0:3]
	s_add_i32 s62, 0, 0x18000
	s_barrier
	s_branch .Lg786_mid
.LBB0_786:
	s_add_u32 s30, s28, 0xfffc0080
	s_addc_u32 s31, s29, -1
	s_cmp_eq_u32 s61, 12
	s_cselect_b32 s35, s19, s31
	s_cselect_b32 s34, s57, s30
	s_cselect_b32 s31, s17, s60
	s_cselect_b32 s30, s58, s59
	s_add_i32 m0, s45, 0xc000
	ds_read_b128 v[168:171], v152
	ds_read_b128 v[172:175], v152 offset:1024
	ds_read_b128 v[176:179], v152 offset:2048
	ds_read_b128 v[180:183], v152 offset:3072
	ds_read_b128 v[184:187], v152 offset:4096
	ds_read_b128 v[188:191], v152 offset:5120
	ds_read_b128 v[192:195], v152 offset:6144
	ds_read_b128 v[196:199], v152 offset:7168
	global_load_lds_dwordx4 v136, s[28:29]
	s_add_i32 m0, s45, 0xe000
	s_nop 0
	global_load_lds_dwordx4 v138, s[28:29]
	s_waitcnt lgkmcnt(8)
	s_barrier
	s_waitcnt lgkmcnt(0)
	s_waitcnt lgkmcnt(0)
	v_mfma_f32_16x16x32_bf16 v[124:127], v[144:147], v[168:171], v[124:127]
	v_mfma_f32_16x16x32_bf16 v[120:123], v[160:163], v[168:171], v[120:123]
	v_mfma_f32_16x16x32_bf16 v[108:111], v[144:147], v[176:179], v[108:111]
	v_mfma_f32_16x16x32_bf16 v[104:107], v[160:163], v[176:179], v[104:107]
	v_mfma_f32_16x16x32_bf16 v[92:95], v[144:147], v[184:187], v[92:95]
	v_mfma_f32_16x16x32_bf16 v[88:91], v[160:163], v[184:187], v[88:91]
	v_mfma_f32_16x16x32_bf16 v[76:79], v[144:147], v[192:195], v[76:79]
	v_mfma_f32_16x16x32_bf16 v[72:75], v[160:163], v[192:195], v[72:75]
	v_mfma_f32_16x16x32_bf16 v[124:127], v[156:159], v[172:175], v[124:127]
	v_mfma_f32_16x16x32_bf16 v[120:123], v[164:167], v[172:175], v[120:123]
	v_mfma_f32_16x16x32_bf16 v[108:111], v[156:159], v[180:183], v[108:111]
	v_mfma_f32_16x16x32_bf16 v[104:107], v[164:167], v[180:183], v[104:107]
	v_mfma_f32_16x16x32_bf16 v[92:95], v[156:159], v[188:191], v[92:95]
	v_mfma_f32_16x16x32_bf16 v[88:91], v[164:167], v[188:191], v[88:91]
	v_mfma_f32_16x16x32_bf16 v[76:79], v[156:159], v[196:199], v[76:79]
	v_mfma_f32_16x16x32_bf16 v[72:75], v[164:167], v[196:199], v[72:75]
	s_barrier
	s_add_i32 s62, s53, s42
	s_add_u32 s80, s30, 0x80
	s_addc_u32 s81, s31, 0
	s_mov_b32 m0, s62
	ds_read_b128 v[200:203], v153
	ds_read_b128 v[204:207], v153 offset:1024
	ds_read_b128 v[208:211], v153 offset:2048
	ds_read_b128 v[212:215], v153 offset:3072
	global_load_lds_dwordx4 v132, s[30:31]
	s_add_i32 m0, s62, 0x2000
	s_nop 0
	global_load_lds_dwordx4 v128, s[30:31]
	s_waitcnt vmcnt(10)
	s_barrier
	s_waitcnt lgkmcnt(0)
	s_waitcnt lgkmcnt(0)
	v_mfma_f32_16x16x32_bf16 v[116:119], v[200:203], v[168:171], v[116:119]
	v_mfma_f32_16x16x32_bf16 v[112:115], v[208:211], v[168:171], v[112:115]
	v_mfma_f32_16x16x32_bf16 v[100:103], v[200:203], v[176:179], v[100:103]
	v_mfma_f32_16x16x32_bf16 v[96:99], v[208:211], v[176:179], v[96:99]
	v_mfma_f32_16x16x32_bf16 v[84:87], v[200:203], v[184:187], v[84:87]
	v_mfma_f32_16x16x32_bf16 v[80:83], v[208:211], v[184:187], v[80:83]
	v_mfma_f32_16x16x32_bf16 v[68:71], v[200:203], v[192:195], v[68:71]
	v_mfma_f32_16x16x32_bf16 v[64:67], v[208:211], v[192:195], v[64:67]
	v_mfma_f32_16x16x32_bf16 v[116:119], v[204:207], v[172:175], v[116:119]
	v_mfma_f32_16x16x32_bf16 v[112:115], v[212:215], v[172:175], v[112:115]
	v_mfma_f32_16x16x32_bf16 v[100:103], v[204:207], v[180:183], v[100:103]
	v_mfma_f32_16x16x32_bf16 v[96:99], v[212:215], v[180:183], v[96:99]
	v_mfma_f32_16x16x32_bf16 v[84:87], v[204:207], v[188:191], v[84:87]
	v_mfma_f32_16x16x32_bf16 v[80:83], v[212:215], v[188:191], v[80:83]
	v_mfma_f32_16x16x32_bf16 v[68:71], v[204:207], v[196:199], v[68:71]
	v_mfma_f32_16x16x32_bf16 v[64:67], v[212:215], v[196:199], v[64:67]
	s_mov_b32 m0, s45
	s_add_u32 s82, s34, 0x80
	s_addc_u32 s83, s35, 0
	s_barrier
	ds_read_b128 v[168:171], v152 offset:16384
	ds_read_b128 v[172:175], v152 offset:17408
	ds_read_b128 v[176:179], v152 offset:18432
	ds_read_b128 v[180:183], v152 offset:19456
	ds_read_b128 v[184:187], v152 offset:20480
	ds_read_b128 v[188:191], v152 offset:21504
	ds_read_b128 v[192:195], v152 offset:22528
	ds_read_b128 v[196:199], v152 offset:23552
	global_load_lds_dwordx4 v134, s[34:35]
	s_mov_b32 m0, s46
	s_nop 0
	global_load_lds_dwordx4 v130, s[34:35]
	s_waitcnt vmcnt(10)
	s_barrier
	s_waitcnt lgkmcnt(0)
	s_waitcnt lgkmcnt(0)
	v_mfma_f32_16x16x32_bf16 v[60:63], v[144:147], v[168:171], v[60:63]
	v_mfma_f32_16x16x32_bf16 v[56:59], v[160:163], v[168:171], v[56:59]
	v_mfma_f32_16x16x32_bf16 v[44:47], v[144:147], v[176:179], v[44:47]
	v_mfma_f32_16x16x32_bf16 v[40:43], v[160:163], v[176:179], v[40:43]
	v_mfma_f32_16x16x32_bf16 v[28:31], v[144:147], v[184:187], v[28:31]
	v_mfma_f32_16x16x32_bf16 v[24:27], v[160:163], v[184:187], v[24:27]
	v_mfma_f32_16x16x32_bf16 v[12:15], v[144:147], v[192:195], v[12:15]
	v_mfma_f32_16x16x32_bf16 v[8:11], v[160:163], v[192:195], v[8:11]
	v_mfma_f32_16x16x32_bf16 v[60:63], v[156:159], v[172:175], v[60:63]
	v_mfma_f32_16x16x32_bf16 v[56:59], v[164:167], v[172:175], v[56:59]
	v_mfma_f32_16x16x32_bf16 v[44:47], v[156:159], v[180:183], v[44:47]
	v_mfma_f32_16x16x32_bf16 v[40:43], v[164:167], v[180:183], v[40:43]
	v_mfma_f32_16x16x32_bf16 v[28:31], v[156:159], v[188:191], v[28:31]
	v_mfma_f32_16x16x32_bf16 v[24:27], v[164:167], v[188:191], v[24:27]
	v_mfma_f32_16x16x32_bf16 v[12:15], v[156:159], v[196:199], v[12:15]
	v_mfma_f32_16x16x32_bf16 v[8:11], v[164:167], v[196:199], v[8:11]
	s_barrier
	v_add_u32_e32 v155, 0x18000, v149
	ds_read_b128 v[144:147], v155
	ds_read_b128 v[156:159], v155 offset:1024
	ds_read_b128 v[160:163], v155 offset:2048
	ds_read_b128 v[164:167], v155 offset:3072
	s_add_u32 s62, s30, 0x40000
	s_addc_u32 s63, s31, 0
	s_add_i32 s64, s54, s42
	s_mov_b32 m0, s64
	s_nop 0
	global_load_lds_dwordx4 v132, s[62:63]
	s_add_i32 m0, s64, 0x2000
	s_nop 0
	global_load_lds_dwordx4 v128, s[62:63]
	s_waitcnt vmcnt(8)
	s_barrier
	v_mfma_f32_16x16x32_bf16 v[52:55], v[200:203], v[168:171], v[52:55]
	v_mfma_f32_16x16x32_bf16 v[48:51], v[208:211], v[168:171], v[48:51]
	v_mfma_f32_16x16x32_bf16 v[36:39], v[200:203], v[176:179], v[36:39]
	v_mfma_f32_16x16x32_bf16 v[32:35], v[208:211], v[176:179], v[32:35]
	v_mfma_f32_16x16x32_bf16 v[20:23], v[200:203], v[184:187], v[20:23]
	v_mfma_f32_16x16x32_bf16 v[16:19], v[208:211], v[184:187], v[16:19]
	v_mfma_f32_16x16x32_bf16 v[4:7], v[200:203], v[192:195], v[4:7]
	v_mfma_f32_16x16x32_bf16 v[0:3], v[208:211], v[192:195], v[0:3]
	v_mfma_f32_16x16x32_bf16 v[52:55], v[204:207], v[172:175], v[52:55]
	v_mfma_f32_16x16x32_bf16 v[48:51], v[212:215], v[172:175], v[48:51]
	v_mfma_f32_16x16x32_bf16 v[36:39], v[204:207], v[180:183], v[36:39]
	v_mfma_f32_16x16x32_bf16 v[32:35], v[212:215], v[180:183], v[32:35]
	v_mfma_f32_16x16x32_bf16 v[20:23], v[204:207], v[188:191], v[20:23]
	v_mfma_f32_16x16x32_bf16 v[16:19], v[212:215], v[188:191], v[16:19]
	v_mfma_f32_16x16x32_bf16 v[4:7], v[204:207], v[196:199], v[4:7]
	v_mfma_f32_16x16x32_bf16 v[0:3], v[212:215], v[196:199], v[0:3]
	s_add_i32 s62, 0, 0x18000
	s_barrier
.Lg786_mid:
	s_add_u32 s34, s34, 0x40000
	s_addc_u32 s35, s35, 0
	s_mov_b32 m0, s47
	ds_read_b128 v[168:171], v152 offset:32768
	ds_read_b128 v[172:175], v152 offset:33792
	ds_read_b128 v[176:179], v152 offset:34816
	ds_read_b128 v[180:183], v152 offset:35840
	ds_read_b128 v[184:187], v152 offset:36864
	ds_read_b128 v[188:191], v152 offset:37888
	ds_read_b128 v[192:195], v152 offset:38912
	ds_read_b128 v[196:199], v152 offset:39936
	global_load_lds_dwordx4 v134, s[34:35]
	s_mov_b32 m0, s48
	s_nop 0
	global_load_lds_dwordx4 v130, s[34:35]
	s_waitcnt lgkmcnt(8)
	s_barrier
	s_waitcnt lgkmcnt(0)
	s_waitcnt lgkmcnt(0)
	v_mfma_f32_16x16x32_bf16 v[124:127], v[144:147], v[168:171], v[124:127]
	v_mfma_f32_16x16x32_bf16 v[120:123], v[160:163], v[168:171], v[120:123]
	v_mfma_f32_16x16x32_bf16 v[108:111], v[144:147], v[176:179], v[108:111]
	v_mfma_f32_16x16x32_bf16 v[104:107], v[160:163], v[176:179], v[104:107]
	v_mfma_f32_16x16x32_bf16 v[92:95], v[144:147], v[184:187], v[92:95]
	v_mfma_f32_16x16x32_bf16 v[88:91], v[160:163], v[184:187], v[88:91]
	v_mfma_f32_16x16x32_bf16 v[76:79], v[144:147], v[192:195], v[76:79]
	v_mfma_f32_16x16x32_bf16 v[72:75], v[160:163], v[192:195], v[72:75]
	v_mfma_f32_16x16x32_bf16 v[124:127], v[156:159], v[172:175], v[124:127]
	v_mfma_f32_16x16x32_bf16 v[120:123], v[164:167], v[172:175], v[120:123]
	v_mfma_f32_16x16x32_bf16 v[108:111], v[156:159], v[180:183], v[108:111]
	v_mfma_f32_16x16x32_bf16 v[104:107], v[164:167], v[180:183], v[104:107]
	v_mfma_f32_16x16x32_bf16 v[92:95], v[156:159], v[188:191], v[92:95]
	v_mfma_f32_16x16x32_bf16 v[88:91], v[164:167], v[188:191], v[88:91]
	v_mfma_f32_16x16x32_bf16 v[76:79], v[156:159], v[196:199], v[76:79]
	v_mfma_f32_16x16x32_bf16 v[72:75], v[164:167], v[196:199], v[72:75]
	s_barrier
	s_add_i32 s34, 0, 0x1c000
	s_add_i32 s35, s62, s42
	v_add_u32_e32 v155, s34, v149
	s_mov_b32 m0, s35
	ds_read_b128 v[200:203], v155
	ds_read_b128 v[204:207], v155 offset:1024
	ds_read_b128 v[208:211], v155 offset:2048
	ds_read_b128 v[212:215], v155 offset:3072
	global_load_lds_dwordx4 v132, s[80:81]
	s_add_i32 m0, s35, 0x2000
	s_nop 0
	global_load_lds_dwordx4 v128, s[80:81]
	s_waitcnt vmcnt(10)
	s_barrier
	s_waitcnt lgkmcnt(0)
	s_waitcnt lgkmcnt(0)
	v_mfma_f32_16x16x32_bf16 v[116:119], v[200:203], v[168:171], v[116:119]
	v_mfma_f32_16x16x32_bf16 v[112:115], v[208:211], v[168:171], v[112:115]
	v_mfma_f32_16x16x32_bf16 v[100:103], v[200:203], v[176:179], v[100:103]
	v_mfma_f32_16x16x32_bf16 v[96:99], v[208:211], v[176:179], v[96:99]
	v_mfma_f32_16x16x32_bf16 v[84:87], v[200:203], v[184:187], v[84:87]
	v_mfma_f32_16x16x32_bf16 v[80:83], v[208:211], v[184:187], v[80:83]
	v_mfma_f32_16x16x32_bf16 v[68:71], v[200:203], v[192:195], v[68:71]
	v_mfma_f32_16x16x32_bf16 v[64:67], v[208:211], v[192:195], v[64:67]
	v_mfma_f32_16x16x32_bf16 v[116:119], v[204:207], v[172:175], v[116:119]
	v_mfma_f32_16x16x32_bf16 v[112:115], v[212:215], v[172:175], v[112:115]
	v_mfma_f32_16x16x32_bf16 v[100:103], v[204:207], v[180:183], v[100:103]
	v_mfma_f32_16x16x32_bf16 v[96:99], v[212:215], v[180:183], v[96:99]
	v_mfma_f32_16x16x32_bf16 v[84:87], v[204:207], v[188:191], v[84:87]
	v_mfma_f32_16x16x32_bf16 v[80:83], v[212:215], v[188:191], v[80:83]
	v_mfma_f32_16x16x32_bf16 v[68:71], v[204:207], v[196:199], v[68:71]
	v_mfma_f32_16x16x32_bf16 v[64:67], v[212:215], v[196:199], v[64:67]
	s_mov_b32 m0, s50
	s_barrier
	ds_read_b128 v[168:171], v152 offset:49152
	ds_read_b128 v[172:175], v152 offset:50176
	ds_read_b128 v[176:179], v152 offset:51200
	ds_read_b128 v[180:183], v152 offset:52224
	ds_read_b128 v[184:187], v152 offset:53248
	ds_read_b128 v[188:191], v152 offset:54272
	ds_read_b128 v[192:195], v152 offset:55296
	ds_read_b128 v[196:199], v152 offset:56320
	global_load_lds_dwordx4 v134, s[82:83]
	s_mov_b32 m0, s51
	s_nop 0
	global_load_lds_dwordx4 v130, s[82:83]
	s_waitcnt vmcnt(10)
	s_barrier
	s_waitcnt lgkmcnt(0)
	s_waitcnt lgkmcnt(0)
	v_mfma_f32_16x16x32_bf16 v[60:63], v[144:147], v[168:171], v[60:63]
	v_mfma_f32_16x16x32_bf16 v[56:59], v[160:163], v[168:171], v[56:59]
	v_mfma_f32_16x16x32_bf16 v[44:47], v[144:147], v[176:179], v[44:47]
	v_mfma_f32_16x16x32_bf16 v[40:43], v[160:163], v[176:179], v[40:43]
	v_mfma_f32_16x16x32_bf16 v[28:31], v[144:147], v[184:187], v[28:31]
	v_mfma_f32_16x16x32_bf16 v[24:27], v[160:163], v[184:187], v[24:27]
	v_mfma_f32_16x16x32_bf16 v[12:15], v[144:147], v[192:195], v[12:15]
	v_mfma_f32_16x16x32_bf16 v[8:11], v[160:163], v[192:195], v[8:11]
	v_mfma_f32_16x16x32_bf16 v[60:63], v[156:159], v[172:175], v[60:63]
	v_mfma_f32_16x16x32_bf16 v[56:59], v[164:167], v[172:175], v[56:59]
	v_mfma_f32_16x16x32_bf16 v[44:47], v[156:159], v[180:183], v[44:47]
	v_mfma_f32_16x16x32_bf16 v[40:43], v[164:167], v[180:183], v[40:43]
	v_mfma_f32_16x16x32_bf16 v[28:31], v[156:159], v[188:191], v[28:31]
	v_mfma_f32_16x16x32_bf16 v[24:27], v[164:167], v[188:191], v[24:27]
	v_mfma_f32_16x16x32_bf16 v[12:15], v[156:159], v[196:199], v[12:15]
	v_mfma_f32_16x16x32_bf16 v[8:11], v[164:167], v[196:199], v[8:11]
	s_barrier
	ds_read_b128 v[144:147], v151
	ds_read_b128 v[156:159], v151 offset:1024
	ds_read_b128 v[160:163], v151 offset:2048
	ds_read_b128 v[164:167], v151 offset:3072
	s_add_u32 s30, s30, 0x40080
	s_addc_u32 s31, s31, 0
	s_add_i32 s34, s34, s42
	s_mov_b32 m0, s34
	s_nop 0
	global_load_lds_dwordx4 v132, s[30:31]
	s_add_i32 m0, s34, 0x2000
	s_nop 0
	global_load_lds_dwordx4 v128, s[30:31]
	s_waitcnt vmcnt(8)
	s_barrier
	v_mfma_f32_16x16x32_bf16 v[52:55], v[200:203], v[168:171], v[52:55]
	v_mfma_f32_16x16x32_bf16 v[48:51], v[208:211], v[168:171], v[48:51]
	v_mfma_f32_16x16x32_bf16 v[36:39], v[200:203], v[176:179], v[36:39]
	v_mfma_f32_16x16x32_bf16 v[32:35], v[208:211], v[176:179], v[32:35]
	v_mfma_f32_16x16x32_bf16 v[20:23], v[200:203], v[184:187], v[20:23]
	v_mfma_f32_16x16x32_bf16 v[16:19], v[208:211], v[184:187], v[16:19]
	v_mfma_f32_16x16x32_bf16 v[4:7], v[200:203], v[192:195], v[4:7]
	v_mfma_f32_16x16x32_bf16 v[0:3], v[208:211], v[192:195], v[0:3]
	v_mfma_f32_16x16x32_bf16 v[52:55], v[204:207], v[172:175], v[52:55]
	v_mfma_f32_16x16x32_bf16 v[48:51], v[212:215], v[172:175], v[48:51]
	v_mfma_f32_16x16x32_bf16 v[36:39], v[204:207], v[180:183], v[36:39]
	v_mfma_f32_16x16x32_bf16 v[32:35], v[212:215], v[180:183], v[32:35]
	v_mfma_f32_16x16x32_bf16 v[20:23], v[204:207], v[188:191], v[20:23]
	v_mfma_f32_16x16x32_bf16 v[16:19], v[212:215], v[188:191], v[16:19]
	v_mfma_f32_16x16x32_bf16 v[4:7], v[204:207], v[196:199], v[4:7]
	v_mfma_f32_16x16x32_bf16 v[0:3], v[212:215], v[196:199], v[0:3]
	s_add_i32 s61, s61, 2
	s_add_u32 s28, s28, 0x100
	s_addc_u32 s29, s29, 0
	s_add_u32 s59, s59, 0x100
	s_addc_u32 s60, s60, 0
	s_cmp_gt_u32 s61, 13
	s_barrier
	s_cbranch_scc0 .LBB0_786
	s_waitcnt lgkmcnt(0)
	s_setprio 0
	v_lshl_add_u32 v146, s8, 8, v148
	v_ashrrev_i32_e32 v147, 31, v146
	v_lshl_or_b32 v144, s56, 8, v150
	v_lshlrev_b64 v[156:157], 11, v[146:147]
	v_ashrrev_i32_e32 v145, 31, v144
	v_lshl_add_u64 v[156:157], s[10:11], 0, v[156:157]
	v_lshl_add_u64 v[166:167], v[144:145], 1, v[156:157]
	global_load_dwordx4 v[158:161], v[166:167], off
	global_load_dwordx4 v[162:165], v[166:167], off offset:256
	s_mov_b64 s[84:85], 0x8000
	s_mov_b64 s[86:87], 0x28000
	v_lshl_add_u64 v[232:233], v[166:167], 0, s[84:85]
	global_load_dwordx4 v[176:179], v[232:233], off
	global_load_dwordx4 v[180:183], v[232:233], off offset:256
	v_lshl_add_u64 v[232:233], v[232:233], 0, s[84:85]
	global_load_dwordx4 v[184:187], v[232:233], off
	global_load_dwordx4 v[188:191], v[232:233], off offset:256
	v_lshl_add_u64 v[232:233], v[232:233], 0, s[84:85]
	global_load_dwordx4 v[192:195], v[232:233], off
	global_load_dwordx4 v[196:199], v[232:233], off offset:256
	v_lshl_add_u64 v[232:233], v[232:233], 0, s[86:87]
	global_load_dwordx4 v[200:203], v[232:233], off
	global_load_dwordx4 v[204:207], v[232:233], off offset:256
	v_lshl_add_u64 v[232:233], v[232:233], 0, s[84:85]
	global_load_dwordx4 v[208:211], v[232:233], off
	global_load_dwordx4 v[212:215], v[232:233], off offset:256
	v_lshl_add_u64 v[232:233], v[232:233], 0, s[84:85]
	global_load_dwordx4 v[216:219], v[232:233], off
	global_load_dwordx4 v[220:223], v[232:233], off offset:256
	v_lshl_add_u64 v[232:233], v[232:233], 0, s[84:85]
	global_load_dwordx4 v[224:227], v[232:233], off
	global_load_dwordx4 v[228:231], v[232:233], off offset:256
	s_cmpk_gt_u32 s37, 0xff
	s_cbranch_scc1 .Lg786_nox
	s_barrier
	s_setprio 1

.Lg893_noy:
	ds_read_b128 v[152:155], v148
	ds_read_b128 v[156:159], v148 offset:1024
	ds_read_b128 v[160:163], v148 offset:2048
	ds_read_b128 v[164:167], v148 offset:3072
	s_add_u32 s26, s20, 0xfffc0080
	s_addc_u32 s27, s21, -1
	s_cmp_eq_u32 s57, 12
	s_cselect_b32 s29, s13, s27
	s_cselect_b32 s28, s53, s26
	s_cselect_b32 s27, s11, s56
	s_cselect_b32 s26, s54, s55
	s_add_i32 m0, s19, 0xc000
	ds_read_b128 v[168:171], v149
	ds_read_b128 v[172:175], v149 offset:1024
	ds_read_b128 v[176:179], v149 offset:2048
	ds_read_b128 v[180:183], v149 offset:3072
	ds_read_b128 v[184:187], v149 offset:4096
	ds_read_b128 v[188:191], v149 offset:5120
	ds_read_b128 v[192:195], v149 offset:6144
	ds_read_b128 v[196:199], v149 offset:7168
	global_load_lds_dwordx4 v136, s[20:21]
	s_add_i32 m0, s19, 0xe000
	s_nop 0
	global_load_lds_dwordx4 v138, s[20:21]
	s_waitcnt lgkmcnt(8)
	s_barrier
	s_waitcnt lgkmcnt(0)
	s_waitcnt lgkmcnt(0)
	v_mfma_f32_16x16x32_bf16 v[124:127], v[152:155], v[168:171], 0
	v_mfma_f32_16x16x32_bf16 v[120:123], v[160:163], v[168:171], 0
	v_mfma_f32_16x16x32_bf16 v[108:111], v[152:155], v[176:179], 0
	v_mfma_f32_16x16x32_bf16 v[104:107], v[160:163], v[176:179], 0
	v_mfma_f32_16x16x32_bf16 v[92:95], v[152:155], v[184:187], 0
	v_mfma_f32_16x16x32_bf16 v[88:91], v[160:163], v[184:187], 0
	v_mfma_f32_16x16x32_bf16 v[76:79], v[152:155], v[192:195], 0
	v_mfma_f32_16x16x32_bf16 v[72:75], v[160:163], v[192:195], 0
	v_mfma_f32_16x16x32_bf16 v[124:127], v[156:159], v[172:175], v[124:127]
	v_mfma_f32_16x16x32_bf16 v[120:123], v[164:167], v[172:175], v[120:123]
	v_mfma_f32_16x16x32_bf16 v[108:111], v[156:159], v[180:183], v[108:111]
	v_mfma_f32_16x16x32_bf16 v[104:107], v[164:167], v[180:183], v[104:107]
	v_mfma_f32_16x16x32_bf16 v[92:95], v[156:159], v[188:191], v[92:95]
	v_mfma_f32_16x16x32_bf16 v[88:91], v[164:167], v[188:191], v[88:91]
	v_mfma_f32_16x16x32_bf16 v[76:79], v[156:159], v[196:199], v[76:79]
	v_mfma_f32_16x16x32_bf16 v[72:75], v[164:167], v[196:199], v[72:75]
	s_barrier
	s_add_i32 s58, s47, s31
	s_add_u32 s80, s26, 0x80
	s_addc_u32 s81, s27, 0
	s_mov_b32 m0, s58
	ds_read_b128 v[200:203], v150
	ds_read_b128 v[204:207], v150 offset:1024
	ds_read_b128 v[208:211], v150 offset:2048
	ds_read_b128 v[212:215], v150 offset:3072
	global_load_lds_dwordx4 v132, s[26:27]
	s_add_i32 m0, s58, 0x2000
	s_nop 0
	global_load_lds_dwordx4 v128, s[26:27]
	s_waitcnt vmcnt(10)
	s_barrier
	s_waitcnt lgkmcnt(0)
	s_waitcnt lgkmcnt(0)
	v_mfma_f32_16x16x32_bf16 v[116:119], v[200:203], v[168:171], 0
	v_mfma_f32_16x16x32_bf16 v[112:115], v[208:211], v[168:171], 0
	v_mfma_f32_16x16x32_bf16 v[100:103], v[200:203], v[176:179], 0
	v_mfma_f32_16x16x32_bf16 v[96:99], v[208:211], v[176:179], 0
	v_mfma_f32_16x16x32_bf16 v[84:87], v[200:203], v[184:187], 0
	v_mfma_f32_16x16x32_bf16 v[80:83], v[208:211], v[184:187], 0
	v_mfma_f32_16x16x32_bf16 v[68:71], v[200:203], v[192:195], 0
	v_mfma_f32_16x16x32_bf16 v[64:67], v[208:211], v[192:195], 0
	v_mfma_f32_16x16x32_bf16 v[116:119], v[204:207], v[172:175], v[116:119]
	v_mfma_f32_16x16x32_bf16 v[112:115], v[212:215], v[172:175], v[112:115]
	v_mfma_f32_16x16x32_bf16 v[100:103], v[204:207], v[180:183], v[100:103]
	v_mfma_f32_16x16x32_bf16 v[96:99], v[212:215], v[180:183], v[96:99]
	v_mfma_f32_16x16x32_bf16 v[84:87], v[204:207], v[188:191], v[84:87]
	v_mfma_f32_16x16x32_bf16 v[80:83], v[212:215], v[188:191], v[80:83]
	v_mfma_f32_16x16x32_bf16 v[68:71], v[204:207], v[196:199], v[68:71]
	v_mfma_f32_16x16x32_bf16 v[64:67], v[212:215], v[196:199], v[64:67]
	s_mov_b32 m0, s19
	s_add_u32 s82, s28, 0x80
	s_addc_u32 s83, s29, 0
	s_barrier
	ds_read_b128 v[168:171], v149 offset:16384
	ds_read_b128 v[172:175], v149 offset:17408
	ds_read_b128 v[176:179], v149 offset:18432
	ds_read_b128 v[180:183], v149 offset:19456
	ds_read_b128 v[184:187], v149 offset:20480
	ds_read_b128 v[188:191], v149 offset:21504
	ds_read_b128 v[192:195], v149 offset:22528
	ds_read_b128 v[196:199], v149 offset:23552
	global_load_lds_dwordx4 v134, s[28:29]
	s_mov_b32 m0, s42
	s_nop 0
	global_load_lds_dwordx4 v130, s[28:29]
	s_waitcnt vmcnt(10)
	s_barrier
	s_waitcnt lgkmcnt(0)
	s_waitcnt lgkmcnt(0)
	v_mfma_f32_16x16x32_bf16 v[60:63], v[152:155], v[168:171], 0
	v_mfma_f32_16x16x32_bf16 v[56:59], v[160:163], v[168:171], 0
	v_mfma_f32_16x16x32_bf16 v[44:47], v[152:155], v[176:179], 0
	v_mfma_f32_16x16x32_bf16 v[40:43], v[160:163], v[176:179], 0
	v_mfma_f32_16x16x32_bf16 v[28:31], v[152:155], v[184:187], 0
	v_mfma_f32_16x16x32_bf16 v[24:27], v[160:163], v[184:187], 0
	v_mfma_f32_16x16x32_bf16 v[12:15], v[152:155], v[192:195], 0
	v_mfma_f32_16x16x32_bf16 v[8:11], v[160:163], v[192:195], 0
	v_mfma_f32_16x16x32_bf16 v[60:63], v[156:159], v[172:175], v[60:63]
	v_mfma_f32_16x16x32_bf16 v[56:59], v[164:167], v[172:175], v[56:59]
	v_mfma_f32_16x16x32_bf16 v[44:47], v[156:159], v[180:183], v[44:47]
	v_mfma_f32_16x16x32_bf16 v[40:43], v[164:167], v[180:183], v[40:43]
	v_mfma_f32_16x16x32_bf16 v[28:31], v[156:159], v[188:191], v[28:31]
	v_mfma_f32_16x16x32_bf16 v[24:27], v[164:167], v[188:191], v[24:27]
	v_mfma_f32_16x16x32_bf16 v[12:15], v[156:159], v[196:199], v[12:15]
	v_mfma_f32_16x16x32_bf16 v[8:11], v[164:167], v[196:199], v[8:11]
	s_barrier
	v_add_u32_e32 v151, 0x18000, v145
	ds_read_b128 v[152:155], v151
	ds_read_b128 v[156:159], v151 offset:1024
	ds_read_b128 v[160:163], v151 offset:2048
	ds_read_b128 v[164:167], v151 offset:3072
	s_add_u32 s58, s26, 0x40000
	s_addc_u32 s59, s27, 0
	s_add_i32 s60, s48, s31
	s_mov_b32 m0, s60
	s_nop 0
	global_load_lds_dwordx4 v132, s[58:59]
	s_add_i32 m0, s60, 0x2000
	s_nop 0
	global_load_lds_dwordx4 v128, s[58:59]
	s_waitcnt vmcnt(8)
	s_barrier
	v_mfma_f32_16x16x32_bf16 v[52:55], v[200:203], v[168:171], 0
	v_mfma_f32_16x16x32_bf16 v[48:51], v[208:211], v[168:171], 0
	v_mfma_f32_16x16x32_bf16 v[36:39], v[200:203], v[176:179], 0
	v_mfma_f32_16x16x32_bf16 v[32:35], v[208:211], v[176:179], 0
	v_mfma_f32_16x16x32_bf16 v[20:23], v[200:203], v[184:187], 0
	v_mfma_f32_16x16x32_bf16 v[16:19], v[208:211], v[184:187], 0
	v_mfma_f32_16x16x32_bf16 v[4:7], v[200:203], v[192:195], 0
	v_mfma_f32_16x16x32_bf16 v[0:3], v[208:211], v[192:195], 0
	v_mfma_f32_16x16x32_bf16 v[52:55], v[204:207], v[172:175], v[52:55]
	v_mfma_f32_16x16x32_bf16 v[48:51], v[212:215], v[172:175], v[48:51]
	v_mfma_f32_16x16x32_bf16 v[36:39], v[204:207], v[180:183], v[36:39]
	v_mfma_f32_16x16x32_bf16 v[32:35], v[212:215], v[180:183], v[32:35]
	v_mfma_f32_16x16x32_bf16 v[20:23], v[204:207], v[188:191], v[20:23]
	v_mfma_f32_16x16x32_bf16 v[16:19], v[212:215], v[188:191], v[16:19]
	v_mfma_f32_16x16x32_bf16 v[4:7], v[204:207], v[196:199], v[4:7]
	v_mfma_f32_16x16x32_bf16 v[0:3], v[212:215], v[196:199], v[0:3]
	s_add_i32 s58, 0, 0x18000
	s_barrier
	s_branch .Lg893_mid
.LBB0_893:
	s_add_u32 s26, s20, 0xfffc0080
	s_addc_u32 s27, s21, -1
	s_cmp_eq_u32 s57, 12
	s_cselect_b32 s29, s13, s27
	s_cselect_b32 s28, s53, s26
	s_cselect_b32 s27, s11, s56
	s_cselect_b32 s26, s54, s55
	s_add_i32 m0, s19, 0xc000
	ds_read_b128 v[168:171], v149
	ds_read_b128 v[172:175], v149 offset:1024
	ds_read_b128 v[176:179], v149 offset:2048
	ds_read_b128 v[180:183], v149 offset:3072
	ds_read_b128 v[184:187], v149 offset:4096
	ds_read_b128 v[188:191], v149 offset:5120
	ds_read_b128 v[192:195], v149 offset:6144
	ds_read_b128 v[196:199], v149 offset:7168
	global_load_lds_dwordx4 v136, s[20:21]
	s_add_i32 m0, s19, 0xe000
	s_nop 0
	global_load_lds_dwordx4 v138, s[20:21]
	s_waitcnt lgkmcnt(8)
	s_barrier
	s_waitcnt lgkmcnt(0)
	s_waitcnt lgkmcnt(0)
	v_mfma_f32_16x16x32_bf16 v[124:127], v[152:155], v[168:171], v[124:127]
	v_mfma_f32_16x16x32_bf16 v[120:123], v[160:163], v[168:171], v[120:123]
	v_mfma_f32_16x16x32_bf16 v[108:111], v[152:155], v[176:179], v[108:111]
	v_mfma_f32_16x16x32_bf16 v[104:107], v[160:163], v[176:179], v[104:107]
	v_mfma_f32_16x16x32_bf16 v[92:95], v[152:155], v[184:187], v[92:95]
	v_mfma_f32_16x16x32_bf16 v[88:91], v[160:163], v[184:187], v[88:91]
	v_mfma_f32_16x16x32_bf16 v[76:79], v[152:155], v[192:195], v[76:79]
	v_mfma_f32_16x16x32_bf16 v[72:75], v[160:163], v[192:195], v[72:75]
	v_mfma_f32_16x16x32_bf16 v[124:127], v[156:159], v[172:175], v[124:127]
	v_mfma_f32_16x16x32_bf16 v[120:123], v[164:167], v[172:175], v[120:123]
	v_mfma_f32_16x16x32_bf16 v[108:111], v[156:159], v[180:183], v[108:111]
	v_mfma_f32_16x16x32_bf16 v[104:107], v[164:167], v[180:183], v[104:107]
	v_mfma_f32_16x16x32_bf16 v[92:95], v[156:159], v[188:191], v[92:95]
	v_mfma_f32_16x16x32_bf16 v[88:91], v[164:167], v[188:191], v[88:91]
	v_mfma_f32_16x16x32_bf16 v[76:79], v[156:159], v[196:199], v[76:79]
	v_mfma_f32_16x16x32_bf16 v[72:75], v[164:167], v[196:199], v[72:75]
	s_barrier
	s_add_i32 s58, s47, s31
	s_add_u32 s80, s26, 0x80
	s_addc_u32 s81, s27, 0
	s_mov_b32 m0, s58
	ds_read_b128 v[200:203], v150
	ds_read_b128 v[204:207], v150 offset:1024
	ds_read_b128 v[208:211], v150 offset:2048
	ds_read_b128 v[212:215], v150 offset:3072
	global_load_lds_dwordx4 v132, s[26:27]
	s_add_i32 m0, s58, 0x2000
	s_nop 0
	global_load_lds_dwordx4 v128, s[26:27]
	s_waitcnt vmcnt(10)
	s_barrier
	s_waitcnt lgkmcnt(0)
	s_waitcnt lgkmcnt(0)
	v_mfma_f32_16x16x32_bf16 v[116:119], v[200:203], v[168:171], v[116:119]
	v_mfma_f32_16x16x32_bf16 v[112:115], v[208:211], v[168:171], v[112:115]
	v_mfma_f32_16x16x32_bf16 v[100:103], v[200:203], v[176:179], v[100:103]
	v_mfma_f32_16x16x32_bf16 v[96:99], v[208:211], v[176:179], v[96:99]
	v_mfma_f32_16x16x32_bf16 v[84:87], v[200:203], v[184:187], v[84:87]
	v_mfma_f32_16x16x32_bf16 v[80:83], v[208:211], v[184:187], v[80:83]
	v_mfma_f32_16x16x32_bf16 v[68:71], v[200:203], v[192:195], v[68:71]
	v_mfma_f32_16x16x32_bf16 v[64:67], v[208:211], v[192:195], v[64:67]
	v_mfma_f32_16x16x32_bf16 v[116:119], v[204:207], v[172:175], v[116:119]
	v_mfma_f32_16x16x32_bf16 v[112:115], v[212:215], v[172:175], v[112:115]
	v_mfma_f32_16x16x32_bf16 v[100:103], v[204:207], v[180:183], v[100:103]
	v_mfma_f32_16x16x32_bf16 v[96:99], v[212:215], v[180:183], v[96:99]
	v_mfma_f32_16x16x32_bf16 v[84:87], v[204:207], v[188:191], v[84:87]
	v_mfma_f32_16x16x32_bf16 v[80:83], v[212:215], v[188:191], v[80:83]
	v_mfma_f32_16x16x32_bf16 v[68:71], v[204:207], v[196:199], v[68:71]
	v_mfma_f32_16x16x32_bf16 v[64:67], v[212:215], v[196:199], v[64:67]
	s_mov_b32 m0, s19
	s_add_u32 s82, s28, 0x80
	s_addc_u32 s83, s29, 0
	s_barrier
	ds_read_b128 v[168:171], v149 offset:16384
	ds_read_b128 v[172:175], v149 offset:17408
	ds_read_b128 v[176:179], v149 offset:18432
	ds_read_b128 v[180:183], v149 offset:19456
	ds_read_b128 v[184:187], v149 offset:20480
	ds_read_b128 v[188:191], v149 offset:21504
	ds_read_b128 v[192:195], v149 offset:22528
	ds_read_b128 v[196:199], v149 offset:23552
	global_load_lds_dwordx4 v134, s[28:29]
	s_mov_b32 m0, s42
	s_nop 0
	global_load_lds_dwordx4 v130, s[28:29]
	s_waitcnt vmcnt(10)
	s_barrier
	s_waitcnt lgkmcnt(0)
	s_waitcnt lgkmcnt(0)
	v_mfma_f32_16x16x32_bf16 v[60:63], v[152:155], v[168:171], v[60:63]
	v_mfma_f32_16x16x32_bf16 v[56:59], v[160:163], v[168:171], v[56:59]
	v_mfma_f32_16x16x32_bf16 v[44:47], v[152:155], v[176:179], v[44:47]
	v_mfma_f32_16x16x32_bf16 v[40:43], v[160:163], v[176:179], v[40:43]
	v_mfma_f32_16x16x32_bf16 v[28:31], v[152:155], v[184:187], v[28:31]
	v_mfma_f32_16x16x32_bf16 v[24:27], v[160:163], v[184:187], v[24:27]
	v_mfma_f32_16x16x32_bf16 v[12:15], v[152:155], v[192:195], v[12:15]
	v_mfma_f32_16x16x32_bf16 v[8:11], v[160:163], v[192:195], v[8:11]
	v_mfma_f32_16x16x32_bf16 v[60:63], v[156:159], v[172:175], v[60:63]
	v_mfma_f32_16x16x32_bf16 v[56:59], v[164:167], v[172:175], v[56:59]
	v_mfma_f32_16x16x32_bf16 v[44:47], v[156:159], v[180:183], v[44:47]
	v_mfma_f32_16x16x32_bf16 v[40:43], v[164:167], v[180:183], v[40:43]
	v_mfma_f32_16x16x32_bf16 v[28:31], v[156:159], v[188:191], v[28:31]
	v_mfma_f32_16x16x32_bf16 v[24:27], v[164:167], v[188:191], v[24:27]
	v_mfma_f32_16x16x32_bf16 v[12:15], v[156:159], v[196:199], v[12:15]
	v_mfma_f32_16x16x32_bf16 v[8:11], v[164:167], v[196:199], v[8:11]
	s_barrier
	v_add_u32_e32 v151, 0x18000, v145
	ds_read_b128 v[152:155], v151
	ds_read_b128 v[156:159], v151 offset:1024
	ds_read_b128 v[160:163], v151 offset:2048
	ds_read_b128 v[164:167], v151 offset:3072
	s_add_u32 s58, s26, 0x40000
	s_addc_u32 s59, s27, 0
	s_add_i32 s60, s48, s31
	s_mov_b32 m0, s60
	s_nop 0
	global_load_lds_dwordx4 v132, s[58:59]
	s_add_i32 m0, s60, 0x2000
	s_nop 0
	global_load_lds_dwordx4 v128, s[58:59]
	s_waitcnt vmcnt(8)
	s_barrier
	v_mfma_f32_16x16x32_bf16 v[52:55], v[200:203], v[168:171], v[52:55]
	v_mfma_f32_16x16x32_bf16 v[48:51], v[208:211], v[168:171], v[48:51]
	v_mfma_f32_16x16x32_bf16 v[36:39], v[200:203], v[176:179], v[36:39]
	v_mfma_f32_16x16x32_bf16 v[32:35], v[208:211], v[176:179], v[32:35]
	v_mfma_f32_16x16x32_bf16 v[20:23], v[200:203], v[184:187], v[20:23]
	v_mfma_f32_16x16x32_bf16 v[16:19], v[208:211], v[184:187], v[16:19]
	v_mfma_f32_16x16x32_bf16 v[4:7], v[200:203], v[192:195], v[4:7]
	v_mfma_f32_16x16x32_bf16 v[0:3], v[208:211], v[192:195], v[0:3]
	v_mfma_f32_16x16x32_bf16 v[52:55], v[204:207], v[172:175], v[52:55]
	v_mfma_f32_16x16x32_bf16 v[48:51], v[212:215], v[172:175], v[48:51]
	v_mfma_f32_16x16x32_bf16 v[36:39], v[204:207], v[180:183], v[36:39]
	v_mfma_f32_16x16x32_bf16 v[32:35], v[212:215], v[180:183], v[32:35]
	v_mfma_f32_16x16x32_bf16 v[20:23], v[204:207], v[188:191], v[20:23]
	v_mfma_f32_16x16x32_bf16 v[16:19], v[212:215], v[188:191], v[16:19]
	v_mfma_f32_16x16x32_bf16 v[4:7], v[204:207], v[196:199], v[4:7]
	v_mfma_f32_16x16x32_bf16 v[0:3], v[212:215], v[196:199], v[0:3]
	s_add_i32 s58, 0, 0x18000
	s_barrier
.Lg893_mid:
	s_add_u32 s28, s28, 0x40000
	s_addc_u32 s29, s29, 0
	s_mov_b32 m0, s43
	ds_read_b128 v[168:171], v149 offset:32768
	ds_read_b128 v[172:175], v149 offset:33792
	ds_read_b128 v[176:179], v149 offset:34816
	ds_read_b128 v[180:183], v149 offset:35840
	ds_read_b128 v[184:187], v149 offset:36864
	ds_read_b128 v[188:191], v149 offset:37888
	ds_read_b128 v[192:195], v149 offset:38912
	ds_read_b128 v[196:199], v149 offset:39936
	global_load_lds_dwordx4 v134, s[28:29]
	s_mov_b32 m0, s44
	s_nop 0
	global_load_lds_dwordx4 v130, s[28:29]
	s_waitcnt lgkmcnt(8)
	s_barrier
	s_waitcnt lgkmcnt(0)
	s_waitcnt lgkmcnt(0)
	v_mfma_f32_16x16x32_bf16 v[124:127], v[152:155], v[168:171], v[124:127]
	v_mfma_f32_16x16x32_bf16 v[120:123], v[160:163], v[168:171], v[120:123]
	v_mfma_f32_16x16x32_bf16 v[108:111], v[152:155], v[176:179], v[108:111]
	v_mfma_f32_16x16x32_bf16 v[104:107], v[160:163], v[176:179], v[104:107]
	v_mfma_f32_16x16x32_bf16 v[92:95], v[152:155], v[184:187], v[92:95]
	v_mfma_f32_16x16x32_bf16 v[88:91], v[160:163], v[184:187], v[88:91]
	v_mfma_f32_16x16x32_bf16 v[76:79], v[152:155], v[192:195], v[76:79]
	v_mfma_f32_16x16x32_bf16 v[72:75], v[160:163], v[192:195], v[72:75]
	v_mfma_f32_16x16x32_bf16 v[124:127], v[156:159], v[172:175], v[124:127]
	v_mfma_f32_16x16x32_bf16 v[120:123], v[164:167], v[172:175], v[120:123]
	v_mfma_f32_16x16x32_bf16 v[108:111], v[156:159], v[180:183], v[108:111]
	v_mfma_f32_16x16x32_bf16 v[104:107], v[164:167], v[180:183], v[104:107]
	v_mfma_f32_16x16x32_bf16 v[92:95], v[156:159], v[188:191], v[92:95]
	v_mfma_f32_16x16x32_bf16 v[88:91], v[164:167], v[188:191], v[88:91]
	v_mfma_f32_16x16x32_bf16 v[76:79], v[156:159], v[196:199], v[76:79]
	v_mfma_f32_16x16x32_bf16 v[72:75], v[164:167], v[196:199], v[72:75]
	s_barrier
	s_add_i32 s28, 0, 0x1c000
	s_add_i32 s29, s58, s31
	v_add_u32_e32 v151, s28, v145
	s_mov_b32 m0, s29
	ds_read_b128 v[200:203], v151
	ds_read_b128 v[204:207], v151 offset:1024
	ds_read_b128 v[208:211], v151 offset:2048
	ds_read_b128 v[212:215], v151 offset:3072
	global_load_lds_dwordx4 v132, s[80:81]
	s_add_i32 m0, s29, 0x2000
	s_nop 0
	global_load_lds_dwordx4 v128, s[80:81]
	s_waitcnt vmcnt(10)
	s_barrier
	s_waitcnt lgkmcnt(0)
	s_waitcnt lgkmcnt(0)
	v_mfma_f32_16x16x32_bf16 v[116:119], v[200:203], v[168:171], v[116:119]
	v_mfma_f32_16x16x32_bf16 v[112:115], v[208:211], v[168:171], v[112:115]
	v_mfma_f32_16x16x32_bf16 v[100:103], v[200:203], v[176:179], v[100:103]
	v_mfma_f32_16x16x32_bf16 v[96:99], v[208:211], v[176:179], v[96:99]
	v_mfma_f32_16x16x32_bf16 v[84:87], v[200:203], v[184:187], v[84:87]
	v_mfma_f32_16x16x32_bf16 v[80:83], v[208:211], v[184:187], v[80:83]
	v_mfma_f32_16x16x32_bf16 v[68:71], v[200:203], v[192:195], v[68:71]
	v_mfma_f32_16x16x32_bf16 v[64:67], v[208:211], v[192:195], v[64:67]
	v_mfma_f32_16x16x32_bf16 v[116:119], v[204:207], v[172:175], v[116:119]
	v_mfma_f32_16x16x32_bf16 v[112:115], v[212:215], v[172:175], v[112:115]
	v_mfma_f32_16x16x32_bf16 v[100:103], v[204:207], v[180:183], v[100:103]
	v_mfma_f32_16x16x32_bf16 v[96:99], v[212:215], v[180:183], v[96:99]
	v_mfma_f32_16x16x32_bf16 v[84:87], v[204:207], v[188:191], v[84:87]
	v_mfma_f32_16x16x32_bf16 v[80:83], v[212:215], v[188:191], v[80:83]
	v_mfma_f32_16x16x32_bf16 v[68:71], v[204:207], v[196:199], v[68:71]
	v_mfma_f32_16x16x32_bf16 v[64:67], v[212:215], v[196:199], v[64:67]
	s_mov_b32 m0, s45
	s_barrier
	ds_read_b128 v[168:171], v149 offset:49152
	ds_read_b128 v[172:175], v149 offset:50176
	ds_read_b128 v[176:179], v149 offset:51200
	ds_read_b128 v[180:183], v149 offset:52224
	ds_read_b128 v[184:187], v149 offset:53248
	ds_read_b128 v[188:191], v149 offset:54272
	ds_read_b128 v[192:195], v149 offset:55296
	ds_read_b128 v[196:199], v149 offset:56320
	global_load_lds_dwordx4 v134, s[82:83]
	s_mov_b32 m0, s46
	s_nop 0
	global_load_lds_dwordx4 v130, s[82:83]
	s_waitcnt vmcnt(10)
	s_barrier
	s_waitcnt lgkmcnt(0)
	s_waitcnt lgkmcnt(0)
	v_mfma_f32_16x16x32_bf16 v[60:63], v[152:155], v[168:171], v[60:63]
	v_mfma_f32_16x16x32_bf16 v[56:59], v[160:163], v[168:171], v[56:59]
	v_mfma_f32_16x16x32_bf16 v[44:47], v[152:155], v[176:179], v[44:47]
	v_mfma_f32_16x16x32_bf16 v[40:43], v[160:163], v[176:179], v[40:43]
	v_mfma_f32_16x16x32_bf16 v[28:31], v[152:155], v[184:187], v[28:31]
	v_mfma_f32_16x16x32_bf16 v[24:27], v[160:163], v[184:187], v[24:27]
	v_mfma_f32_16x16x32_bf16 v[12:15], v[152:155], v[192:195], v[12:15]
	v_mfma_f32_16x16x32_bf16 v[8:11], v[160:163], v[192:195], v[8:11]
	v_mfma_f32_16x16x32_bf16 v[60:63], v[156:159], v[172:175], v[60:63]
	v_mfma_f32_16x16x32_bf16 v[56:59], v[164:167], v[172:175], v[56:59]
	v_mfma_f32_16x16x32_bf16 v[44:47], v[156:159], v[180:183], v[44:47]
	v_mfma_f32_16x16x32_bf16 v[40:43], v[164:167], v[180:183], v[40:43]
	v_mfma_f32_16x16x32_bf16 v[28:31], v[156:159], v[188:191], v[28:31]
	v_mfma_f32_16x16x32_bf16 v[24:27], v[164:167], v[188:191], v[24:27]
	v_mfma_f32_16x16x32_bf16 v[12:15], v[156:159], v[196:199], v[12:15]
	v_mfma_f32_16x16x32_bf16 v[8:11], v[164:167], v[196:199], v[8:11]
	s_barrier
	ds_read_b128 v[152:155], v148
	ds_read_b128 v[156:159], v148 offset:1024
	ds_read_b128 v[160:163], v148 offset:2048
	ds_read_b128 v[164:167], v148 offset:3072
	s_add_u32 s26, s26, 0x40080
	s_addc_u32 s27, s27, 0
	s_add_i32 s28, s28, s31
	s_mov_b32 m0, s28
	s_nop 0
	global_load_lds_dwordx4 v132, s[26:27]
	s_add_i32 m0, s28, 0x2000
	s_nop 0
	global_load_lds_dwordx4 v128, s[26:27]
	s_waitcnt vmcnt(8)
	s_barrier
	v_mfma_f32_16x16x32_bf16 v[52:55], v[200:203], v[168:171], v[52:55]
	v_mfma_f32_16x16x32_bf16 v[48:51], v[208:211], v[168:171], v[48:51]
	v_mfma_f32_16x16x32_bf16 v[36:39], v[200:203], v[176:179], v[36:39]
	v_mfma_f32_16x16x32_bf16 v[32:35], v[208:211], v[176:179], v[32:35]
	v_mfma_f32_16x16x32_bf16 v[20:23], v[200:203], v[184:187], v[20:23]
	v_mfma_f32_16x16x32_bf16 v[16:19], v[208:211], v[184:187], v[16:19]
	v_mfma_f32_16x16x32_bf16 v[4:7], v[200:203], v[192:195], v[4:7]
	v_mfma_f32_16x16x32_bf16 v[0:3], v[208:211], v[192:195], v[0:3]
	v_mfma_f32_16x16x32_bf16 v[52:55], v[204:207], v[172:175], v[52:55]
	v_mfma_f32_16x16x32_bf16 v[48:51], v[212:215], v[172:175], v[48:51]
	v_mfma_f32_16x16x32_bf16 v[36:39], v[204:207], v[180:183], v[36:39]
	v_mfma_f32_16x16x32_bf16 v[32:35], v[212:215], v[180:183], v[32:35]
	v_mfma_f32_16x16x32_bf16 v[20:23], v[204:207], v[188:191], v[20:23]
	v_mfma_f32_16x16x32_bf16 v[16:19], v[212:215], v[188:191], v[16:19]
	v_mfma_f32_16x16x32_bf16 v[4:7], v[204:207], v[196:199], v[4:7]
	v_mfma_f32_16x16x32_bf16 v[0:3], v[212:215], v[196:199], v[0:3]
	s_add_i32 s57, s57, 2
	s_add_u32 s20, s20, 0x100
	s_addc_u32 s21, s21, 0
	s_add_u32 s55, s55, 0x100
	s_addc_u32 s56, s56, 0
	s_cmp_gt_u32 s57, 13
	s_barrier
	s_cbranch_scc0 .LBB0_893
	s_waitcnt lgkmcnt(0)
	s_setprio 0
	s_cmpk_gt_u32 s30, 0xff
	s_cbranch_scc1 .Lg893_nox
	s_barrier
	s_setprio 1

.Lg973_noy:
	ds_read_b128 v[146:149], v203
	ds_read_b128 v[150:153], v203 offset:1024
	ds_read_b128 v[154:157], v203 offset:2048
	ds_read_b128 v[158:161], v203 offset:3072
	s_add_u32 s22, s20, 0x100
	s_addc_u32 s23, s21, 0
	s_cmp_eq_u32 s56, 40
	s_cselect_b32 s27, s5, s23
	s_cselect_b32 s26, s4, s22
	s_cselect_b32 s25, s7, s55
	s_cselect_b32 s24, s6, s54
	s_add_i32 m0, s37, 0xc000
	ds_read_b128 v[162:165], v204
	ds_read_b128 v[166:169], v204 offset:1024
	ds_read_b128 v[170:173], v204 offset:2048
	ds_read_b128 v[174:177], v204 offset:3072
	ds_read_b128 v[178:181], v204 offset:4096
	ds_read_b128 v[182:185], v204 offset:5120
	ds_read_b128 v[186:189], v204 offset:6144
	ds_read_b128 v[190:193], v204 offset:7168
	global_load_lds_dwordx4 v138, s[20:21]
	s_add_i32 m0, s37, 0xe000
	s_nop 0
	global_load_lds_dwordx4 v140, s[20:21]
	s_waitcnt lgkmcnt(8)
	s_barrier
	s_waitcnt lgkmcnt(0)
	s_waitcnt lgkmcnt(0)
	v_mfma_f32_16x16x32_bf16 v[124:127], v[146:149], v[162:165], 0
	v_mfma_f32_16x16x32_bf16 v[120:123], v[154:157], v[162:165], 0
	v_mfma_f32_16x16x32_bf16 v[108:111], v[146:149], v[170:173], 0
	v_mfma_f32_16x16x32_bf16 v[104:107], v[154:157], v[170:173], 0
	v_mfma_f32_16x16x32_bf16 v[92:95], v[146:149], v[178:181], 0
	v_mfma_f32_16x16x32_bf16 v[88:91], v[154:157], v[178:181], 0
	v_mfma_f32_16x16x32_bf16 v[76:79], v[146:149], v[186:189], 0
	v_mfma_f32_16x16x32_bf16 v[72:75], v[154:157], v[186:189], 0
	v_mfma_f32_16x16x32_bf16 v[124:127], v[150:153], v[166:169], v[124:127]
	v_mfma_f32_16x16x32_bf16 v[120:123], v[158:161], v[166:169], v[120:123]
	v_mfma_f32_16x16x32_bf16 v[108:111], v[150:153], v[174:177], v[108:111]
	v_mfma_f32_16x16x32_bf16 v[104:107], v[158:161], v[174:177], v[104:107]
	v_mfma_f32_16x16x32_bf16 v[92:95], v[150:153], v[182:185], v[92:95]
	v_mfma_f32_16x16x32_bf16 v[88:91], v[158:161], v[182:185], v[88:91]
	v_mfma_f32_16x16x32_bf16 v[76:79], v[150:153], v[190:193], v[76:79]
	v_mfma_f32_16x16x32_bf16 v[72:75], v[158:161], v[190:193], v[72:75]
	s_barrier
	s_add_i32 s20, s47, s36
	s_add_u32 s80, s24, 0x80
	s_addc_u32 s81, s25, 0
	s_mov_b32 m0, s20
	ds_read_b128 v[194:197], v205
	ds_read_b128 v[208:211], v205 offset:1024
	ds_read_b128 v[212:215], v205 offset:2048
	ds_read_b128 v[216:219], v205 offset:3072
	global_load_lds_dwordx4 v130, s[24:25]
	s_add_i32 m0, s20, 0x2000
	s_nop 0
	global_load_lds_dwordx4 v134, s[24:25]
	s_waitcnt vmcnt(10)
	s_barrier
	s_waitcnt lgkmcnt(0)
	s_waitcnt lgkmcnt(0)
	v_mfma_f32_16x16x32_bf16 v[116:119], v[194:197], v[162:165], 0
	v_mfma_f32_16x16x32_bf16 v[112:115], v[212:215], v[162:165], 0
	v_mfma_f32_16x16x32_bf16 v[100:103], v[194:197], v[170:173], 0
	v_mfma_f32_16x16x32_bf16 v[96:99], v[212:215], v[170:173], 0
	v_mfma_f32_16x16x32_bf16 v[84:87], v[194:197], v[178:181], 0
	v_mfma_f32_16x16x32_bf16 v[80:83], v[212:215], v[178:181], 0
	v_mfma_f32_16x16x32_bf16 v[68:71], v[194:197], v[186:189], 0
	v_mfma_f32_16x16x32_bf16 v[64:67], v[212:215], v[186:189], 0
	v_mfma_f32_16x16x32_bf16 v[116:119], v[208:211], v[166:169], v[116:119]
	v_mfma_f32_16x16x32_bf16 v[112:115], v[216:219], v[166:169], v[112:115]
	v_mfma_f32_16x16x32_bf16 v[100:103], v[208:211], v[174:177], v[100:103]
	v_mfma_f32_16x16x32_bf16 v[96:99], v[216:219], v[174:177], v[96:99]
	v_mfma_f32_16x16x32_bf16 v[84:87], v[208:211], v[182:185], v[84:87]
	v_mfma_f32_16x16x32_bf16 v[80:83], v[216:219], v[182:185], v[80:83]
	v_mfma_f32_16x16x32_bf16 v[68:71], v[208:211], v[190:193], v[68:71]
	v_mfma_f32_16x16x32_bf16 v[64:67], v[216:219], v[190:193], v[64:67]
	s_mov_b32 m0, s37
	s_add_u32 s82, s26, 0x80
	s_addc_u32 s83, s27, 0
	s_barrier
	ds_read_b128 v[162:165], v204 offset:16384
	ds_read_b128 v[166:169], v204 offset:17408
	ds_read_b128 v[170:173], v204 offset:18432
	ds_read_b128 v[174:177], v204 offset:19456
	ds_read_b128 v[178:181], v204 offset:20480
	ds_read_b128 v[182:185], v204 offset:21504
	ds_read_b128 v[186:189], v204 offset:22528
	ds_read_b128 v[190:193], v204 offset:23552
	global_load_lds_dwordx4 v128, s[26:27]
	s_mov_b32 m0, s38
	s_nop 0
	global_load_lds_dwordx4 v132, s[26:27]
	s_waitcnt vmcnt(10)
	s_barrier
	s_waitcnt lgkmcnt(0)
	s_waitcnt lgkmcnt(0)
	v_mfma_f32_16x16x32_bf16 v[60:63], v[146:149], v[162:165], 0
	v_mfma_f32_16x16x32_bf16 v[56:59], v[154:157], v[162:165], 0
	v_mfma_f32_16x16x32_bf16 v[44:47], v[146:149], v[170:173], 0
	v_mfma_f32_16x16x32_bf16 v[40:43], v[154:157], v[170:173], 0
	v_mfma_f32_16x16x32_bf16 v[28:31], v[146:149], v[178:181], 0
	v_mfma_f32_16x16x32_bf16 v[24:27], v[154:157], v[178:181], 0
	v_mfma_f32_16x16x32_bf16 v[12:15], v[146:149], v[186:189], 0
	v_mfma_f32_16x16x32_bf16 v[8:11], v[154:157], v[186:189], 0
	v_mfma_f32_16x16x32_bf16 v[60:63], v[150:153], v[166:169], v[60:63]
	v_mfma_f32_16x16x32_bf16 v[56:59], v[158:161], v[166:169], v[56:59]
	v_mfma_f32_16x16x32_bf16 v[44:47], v[150:153], v[174:177], v[44:47]
	v_mfma_f32_16x16x32_bf16 v[40:43], v[158:161], v[174:177], v[40:43]
	v_mfma_f32_16x16x32_bf16 v[28:31], v[150:153], v[182:185], v[28:31]
	v_mfma_f32_16x16x32_bf16 v[24:27], v[158:161], v[182:185], v[24:27]
	v_mfma_f32_16x16x32_bf16 v[12:15], v[150:153], v[190:193], v[12:15]
	v_mfma_f32_16x16x32_bf16 v[8:11], v[158:161], v[190:193], v[8:11]
	s_barrier
	v_add_u32_e32 v158, 0x18000, v201
	ds_read_b128 v[146:149], v158
	ds_read_b128 v[150:153], v158 offset:1024
	ds_read_b128 v[154:157], v158 offset:2048
	ds_read_b128 v[158:161], v158 offset:3072
	s_add_u32 s20, s24, 0xb0000
	s_addc_u32 s21, s25, 0
	s_add_i32 s57, s48, s36
	s_mov_b32 m0, s57
	s_nop 0
	global_load_lds_dwordx4 v130, s[20:21]
	s_add_i32 m0, s57, 0x2000
	s_nop 0
	global_load_lds_dwordx4 v134, s[20:21]
	s_waitcnt vmcnt(8)
	s_barrier
	v_mfma_f32_16x16x32_bf16 v[52:55], v[194:197], v[162:165], 0
	v_mfma_f32_16x16x32_bf16 v[48:51], v[212:215], v[162:165], 0
	v_mfma_f32_16x16x32_bf16 v[36:39], v[194:197], v[170:173], 0
	v_mfma_f32_16x16x32_bf16 v[32:35], v[212:215], v[170:173], 0
	v_mfma_f32_16x16x32_bf16 v[20:23], v[194:197], v[178:181], 0
	v_mfma_f32_16x16x32_bf16 v[16:19], v[212:215], v[178:181], 0
	v_mfma_f32_16x16x32_bf16 v[4:7], v[194:197], v[186:189], 0
	v_mfma_f32_16x16x32_bf16 v[0:3], v[212:215], v[186:189], 0
	v_mfma_f32_16x16x32_bf16 v[52:55], v[208:211], v[166:169], v[52:55]
	v_mfma_f32_16x16x32_bf16 v[48:51], v[216:219], v[166:169], v[48:51]
	v_mfma_f32_16x16x32_bf16 v[36:39], v[208:211], v[174:177], v[36:39]
	v_mfma_f32_16x16x32_bf16 v[32:35], v[216:219], v[174:177], v[32:35]
	v_mfma_f32_16x16x32_bf16 v[20:23], v[208:211], v[182:185], v[20:23]
	v_mfma_f32_16x16x32_bf16 v[16:19], v[216:219], v[182:185], v[16:19]
	v_mfma_f32_16x16x32_bf16 v[4:7], v[208:211], v[190:193], v[4:7]
	v_mfma_f32_16x16x32_bf16 v[0:3], v[216:219], v[190:193], v[0:3]
	s_add_i32 s57, 0, 0x18000
	s_barrier
	s_branch .Lg973_mid
.LBB0_973:
	s_add_u32 s22, s20, 0x100
	s_addc_u32 s23, s21, 0
	s_cmp_eq_u32 s56, 40
	s_cselect_b32 s27, s5, s23
	s_cselect_b32 s26, s4, s22
	s_cselect_b32 s25, s7, s55
	s_cselect_b32 s24, s6, s54
	s_add_i32 m0, s37, 0xc000
	ds_read_b128 v[162:165], v204
	ds_read_b128 v[166:169], v204 offset:1024
	ds_read_b128 v[170:173], v204 offset:2048
	ds_read_b128 v[174:177], v204 offset:3072
	ds_read_b128 v[178:181], v204 offset:4096
	ds_read_b128 v[182:185], v204 offset:5120
	ds_read_b128 v[186:189], v204 offset:6144
	ds_read_b128 v[190:193], v204 offset:7168
	global_load_lds_dwordx4 v138, s[20:21]
	s_add_i32 m0, s37, 0xe000
	s_nop 0
	global_load_lds_dwordx4 v140, s[20:21]
	s_waitcnt lgkmcnt(8)
	s_barrier
	s_waitcnt lgkmcnt(0)
	s_waitcnt lgkmcnt(0)
	v_mfma_f32_16x16x32_bf16 v[124:127], v[146:149], v[162:165], v[124:127]
	v_mfma_f32_16x16x32_bf16 v[120:123], v[154:157], v[162:165], v[120:123]
	v_mfma_f32_16x16x32_bf16 v[108:111], v[146:149], v[170:173], v[108:111]
	v_mfma_f32_16x16x32_bf16 v[104:107], v[154:157], v[170:173], v[104:107]
	v_mfma_f32_16x16x32_bf16 v[92:95], v[146:149], v[178:181], v[92:95]
	v_mfma_f32_16x16x32_bf16 v[88:91], v[154:157], v[178:181], v[88:91]
	v_mfma_f32_16x16x32_bf16 v[76:79], v[146:149], v[186:189], v[76:79]
	v_mfma_f32_16x16x32_bf16 v[72:75], v[154:157], v[186:189], v[72:75]
	v_mfma_f32_16x16x32_bf16 v[124:127], v[150:153], v[166:169], v[124:127]
	v_mfma_f32_16x16x32_bf16 v[120:123], v[158:161], v[166:169], v[120:123]
	v_mfma_f32_16x16x32_bf16 v[108:111], v[150:153], v[174:177], v[108:111]
	v_mfma_f32_16x16x32_bf16 v[104:107], v[158:161], v[174:177], v[104:107]
	v_mfma_f32_16x16x32_bf16 v[92:95], v[150:153], v[182:185], v[92:95]
	v_mfma_f32_16x16x32_bf16 v[88:91], v[158:161], v[182:185], v[88:91]
	v_mfma_f32_16x16x32_bf16 v[76:79], v[150:153], v[190:193], v[76:79]
	v_mfma_f32_16x16x32_bf16 v[72:75], v[158:161], v[190:193], v[72:75]
	s_barrier
	s_add_i32 s20, s47, s36
	s_add_u32 s80, s24, 0x80
	s_addc_u32 s81, s25, 0
	s_mov_b32 m0, s20
	ds_read_b128 v[194:197], v205
	ds_read_b128 v[208:211], v205 offset:1024
	ds_read_b128 v[212:215], v205 offset:2048
	ds_read_b128 v[216:219], v205 offset:3072
	global_load_lds_dwordx4 v130, s[24:25]
	s_add_i32 m0, s20, 0x2000
	s_nop 0
	global_load_lds_dwordx4 v134, s[24:25]
	s_waitcnt vmcnt(10)
	s_barrier
	s_waitcnt lgkmcnt(0)
	s_waitcnt lgkmcnt(0)
	v_mfma_f32_16x16x32_bf16 v[116:119], v[194:197], v[162:165], v[116:119]
	v_mfma_f32_16x16x32_bf16 v[112:115], v[212:215], v[162:165], v[112:115]
	v_mfma_f32_16x16x32_bf16 v[100:103], v[194:197], v[170:173], v[100:103]
	v_mfma_f32_16x16x32_bf16 v[96:99], v[212:215], v[170:173], v[96:99]
	v_mfma_f32_16x16x32_bf16 v[84:87], v[194:197], v[178:181], v[84:87]
	v_mfma_f32_16x16x32_bf16 v[80:83], v[212:215], v[178:181], v[80:83]
	v_mfma_f32_16x16x32_bf16 v[68:71], v[194:197], v[186:189], v[68:71]
	v_mfma_f32_16x16x32_bf16 v[64:67], v[212:215], v[186:189], v[64:67]
	v_mfma_f32_16x16x32_bf16 v[116:119], v[208:211], v[166:169], v[116:119]
	v_mfma_f32_16x16x32_bf16 v[112:115], v[216:219], v[166:169], v[112:115]
	v_mfma_f32_16x16x32_bf16 v[100:103], v[208:211], v[174:177], v[100:103]
	v_mfma_f32_16x16x32_bf16 v[96:99], v[216:219], v[174:177], v[96:99]
	v_mfma_f32_16x16x32_bf16 v[84:87], v[208:211], v[182:185], v[84:87]
	v_mfma_f32_16x16x32_bf16 v[80:83], v[216:219], v[182:185], v[80:83]
	v_mfma_f32_16x16x32_bf16 v[68:71], v[208:211], v[190:193], v[68:71]
	v_mfma_f32_16x16x32_bf16 v[64:67], v[216:219], v[190:193], v[64:67]
	s_mov_b32 m0, s37
	s_add_u32 s82, s26, 0x80
	s_addc_u32 s83, s27, 0
	s_barrier
	ds_read_b128 v[162:165], v204 offset:16384
	ds_read_b128 v[166:169], v204 offset:17408
	ds_read_b128 v[170:173], v204 offset:18432
	ds_read_b128 v[174:177], v204 offset:19456
	ds_read_b128 v[178:181], v204 offset:20480
	ds_read_b128 v[182:185], v204 offset:21504
	ds_read_b128 v[186:189], v204 offset:22528
	ds_read_b128 v[190:193], v204 offset:23552
	global_load_lds_dwordx4 v128, s[26:27]
	s_mov_b32 m0, s38
	s_nop 0
	global_load_lds_dwordx4 v132, s[26:27]
	s_waitcnt vmcnt(10)
	s_barrier
	s_waitcnt lgkmcnt(0)
	s_waitcnt lgkmcnt(0)
	v_mfma_f32_16x16x32_bf16 v[60:63], v[146:149], v[162:165], v[60:63]
	v_mfma_f32_16x16x32_bf16 v[56:59], v[154:157], v[162:165], v[56:59]
	v_mfma_f32_16x16x32_bf16 v[44:47], v[146:149], v[170:173], v[44:47]
	v_mfma_f32_16x16x32_bf16 v[40:43], v[154:157], v[170:173], v[40:43]
	v_mfma_f32_16x16x32_bf16 v[28:31], v[146:149], v[178:181], v[28:31]
	v_mfma_f32_16x16x32_bf16 v[24:27], v[154:157], v[178:181], v[24:27]
	v_mfma_f32_16x16x32_bf16 v[12:15], v[146:149], v[186:189], v[12:15]
	v_mfma_f32_16x16x32_bf16 v[8:11], v[154:157], v[186:189], v[8:11]
	v_mfma_f32_16x16x32_bf16 v[60:63], v[150:153], v[166:169], v[60:63]
	v_mfma_f32_16x16x32_bf16 v[56:59], v[158:161], v[166:169], v[56:59]
	v_mfma_f32_16x16x32_bf16 v[44:47], v[150:153], v[174:177], v[44:47]
	v_mfma_f32_16x16x32_bf16 v[40:43], v[158:161], v[174:177], v[40:43]
	v_mfma_f32_16x16x32_bf16 v[28:31], v[150:153], v[182:185], v[28:31]
	v_mfma_f32_16x16x32_bf16 v[24:27], v[158:161], v[182:185], v[24:27]
	v_mfma_f32_16x16x32_bf16 v[12:15], v[150:153], v[190:193], v[12:15]
	v_mfma_f32_16x16x32_bf16 v[8:11], v[158:161], v[190:193], v[8:11]
	s_barrier
	v_add_u32_e32 v158, 0x18000, v201
	ds_read_b128 v[146:149], v158
	ds_read_b128 v[150:153], v158 offset:1024
	ds_read_b128 v[154:157], v158 offset:2048
	ds_read_b128 v[158:161], v158 offset:3072
	s_add_u32 s20, s24, 0xb0000
	s_addc_u32 s21, s25, 0
	s_add_i32 s57, s48, s36
	s_mov_b32 m0, s57
	s_nop 0
	global_load_lds_dwordx4 v130, s[20:21]
	s_add_i32 m0, s57, 0x2000
	s_nop 0
	global_load_lds_dwordx4 v134, s[20:21]
	s_waitcnt vmcnt(8)
	s_barrier
	v_mfma_f32_16x16x32_bf16 v[52:55], v[194:197], v[162:165], v[52:55]
	v_mfma_f32_16x16x32_bf16 v[48:51], v[212:215], v[162:165], v[48:51]
	v_mfma_f32_16x16x32_bf16 v[36:39], v[194:197], v[170:173], v[36:39]
	v_mfma_f32_16x16x32_bf16 v[32:35], v[212:215], v[170:173], v[32:35]
	v_mfma_f32_16x16x32_bf16 v[20:23], v[194:197], v[178:181], v[20:23]
	v_mfma_f32_16x16x32_bf16 v[16:19], v[212:215], v[178:181], v[16:19]
	v_mfma_f32_16x16x32_bf16 v[4:7], v[194:197], v[186:189], v[4:7]
	v_mfma_f32_16x16x32_bf16 v[0:3], v[212:215], v[186:189], v[0:3]
	v_mfma_f32_16x16x32_bf16 v[52:55], v[208:211], v[166:169], v[52:55]
	v_mfma_f32_16x16x32_bf16 v[48:51], v[216:219], v[166:169], v[48:51]
	v_mfma_f32_16x16x32_bf16 v[36:39], v[208:211], v[174:177], v[36:39]
	v_mfma_f32_16x16x32_bf16 v[32:35], v[216:219], v[174:177], v[32:35]
	v_mfma_f32_16x16x32_bf16 v[20:23], v[208:211], v[182:185], v[20:23]
	v_mfma_f32_16x16x32_bf16 v[16:19], v[216:219], v[182:185], v[16:19]
	v_mfma_f32_16x16x32_bf16 v[4:7], v[208:211], v[190:193], v[4:7]
	v_mfma_f32_16x16x32_bf16 v[0:3], v[216:219], v[190:193], v[0:3]
	s_add_i32 s57, 0, 0x18000
	s_barrier
.Lg973_mid:
	s_add_u32 s20, s26, 0xb0000
	s_addc_u32 s21, s27, 0
	s_mov_b32 m0, s39
	ds_read_b128 v[162:165], v204 offset:32768
	ds_read_b128 v[166:169], v204 offset:33792
	ds_read_b128 v[170:173], v204 offset:34816
	ds_read_b128 v[174:177], v204 offset:35840
	ds_read_b128 v[178:181], v204 offset:36864
	ds_read_b128 v[182:185], v204 offset:37888
	ds_read_b128 v[186:189], v204 offset:38912
	ds_read_b128 v[190:193], v204 offset:39936
	global_load_lds_dwordx4 v128, s[20:21]
	s_mov_b32 m0, s40
	s_nop 0
	global_load_lds_dwordx4 v132, s[20:21]
	s_waitcnt lgkmcnt(8)
	s_barrier
	s_waitcnt lgkmcnt(0)
	s_waitcnt lgkmcnt(0)
	v_mfma_f32_16x16x32_bf16 v[124:127], v[146:149], v[162:165], v[124:127]
	v_mfma_f32_16x16x32_bf16 v[120:123], v[154:157], v[162:165], v[120:123]
	v_mfma_f32_16x16x32_bf16 v[108:111], v[146:149], v[170:173], v[108:111]
	v_mfma_f32_16x16x32_bf16 v[104:107], v[154:157], v[170:173], v[104:107]
	v_mfma_f32_16x16x32_bf16 v[92:95], v[146:149], v[178:181], v[92:95]
	v_mfma_f32_16x16x32_bf16 v[88:91], v[154:157], v[178:181], v[88:91]
	v_mfma_f32_16x16x32_bf16 v[76:79], v[146:149], v[186:189], v[76:79]
	v_mfma_f32_16x16x32_bf16 v[72:75], v[154:157], v[186:189], v[72:75]
	v_mfma_f32_16x16x32_bf16 v[124:127], v[150:153], v[166:169], v[124:127]
	v_mfma_f32_16x16x32_bf16 v[120:123], v[158:161], v[166:169], v[120:123]
	v_mfma_f32_16x16x32_bf16 v[108:111], v[150:153], v[174:177], v[108:111]
	v_mfma_f32_16x16x32_bf16 v[104:107], v[158:161], v[174:177], v[104:107]
	v_mfma_f32_16x16x32_bf16 v[92:95], v[150:153], v[182:185], v[92:95]
	v_mfma_f32_16x16x32_bf16 v[88:91], v[158:161], v[182:185], v[88:91]
	v_mfma_f32_16x16x32_bf16 v[76:79], v[150:153], v[190:193], v[76:79]
	v_mfma_f32_16x16x32_bf16 v[72:75], v[158:161], v[190:193], v[72:75]
	s_barrier
	s_add_i32 s26, 0, 0x1c000
	s_add_i32 s20, s57, s36
	v_add_u32_e32 v216, s26, v201
	s_mov_b32 m0, s20
	ds_read_b128 v[194:197], v216
	ds_read_b128 v[208:211], v216 offset:1024
	ds_read_b128 v[212:215], v216 offset:2048
	ds_read_b128 v[216:219], v216 offset:3072
	global_load_lds_dwordx4 v130, s[80:81]
	s_add_i32 m0, s20, 0x2000
	s_nop 0
	global_load_lds_dwordx4 v134, s[80:81]
	s_waitcnt vmcnt(10)
	s_barrier
	s_waitcnt lgkmcnt(0)
	s_waitcnt lgkmcnt(0)
	v_mfma_f32_16x16x32_bf16 v[116:119], v[194:197], v[162:165], v[116:119]
	v_mfma_f32_16x16x32_bf16 v[112:115], v[212:215], v[162:165], v[112:115]
	v_mfma_f32_16x16x32_bf16 v[100:103], v[194:197], v[170:173], v[100:103]
	v_mfma_f32_16x16x32_bf16 v[96:99], v[212:215], v[170:173], v[96:99]
	v_mfma_f32_16x16x32_bf16 v[84:87], v[194:197], v[178:181], v[84:87]
	v_mfma_f32_16x16x32_bf16 v[80:83], v[212:215], v[178:181], v[80:83]
	v_mfma_f32_16x16x32_bf16 v[68:71], v[194:197], v[186:189], v[68:71]
	v_mfma_f32_16x16x32_bf16 v[64:67], v[212:215], v[186:189], v[64:67]
	v_mfma_f32_16x16x32_bf16 v[116:119], v[208:211], v[166:169], v[116:119]
	v_mfma_f32_16x16x32_bf16 v[112:115], v[216:219], v[166:169], v[112:115]
	v_mfma_f32_16x16x32_bf16 v[100:103], v[208:211], v[174:177], v[100:103]
	v_mfma_f32_16x16x32_bf16 v[96:99], v[216:219], v[174:177], v[96:99]
	v_mfma_f32_16x16x32_bf16 v[84:87], v[208:211], v[182:185], v[84:87]
	v_mfma_f32_16x16x32_bf16 v[80:83], v[216:219], v[182:185], v[80:83]
	v_mfma_f32_16x16x32_bf16 v[68:71], v[208:211], v[190:193], v[68:71]
	v_mfma_f32_16x16x32_bf16 v[64:67], v[216:219], v[190:193], v[64:67]
	s_mov_b32 m0, s42
	s_barrier
	ds_read_b128 v[162:165], v204 offset:49152
	ds_read_b128 v[166:169], v204 offset:50176
	ds_read_b128 v[170:173], v204 offset:51200
	ds_read_b128 v[174:177], v204 offset:52224
	ds_read_b128 v[178:181], v204 offset:53248
	ds_read_b128 v[182:185], v204 offset:54272
	ds_read_b128 v[186:189], v204 offset:55296
	ds_read_b128 v[190:193], v204 offset:56320
	global_load_lds_dwordx4 v128, s[82:83]
	s_mov_b32 m0, s43
	s_nop 0
	global_load_lds_dwordx4 v132, s[82:83]
	s_waitcnt vmcnt(10)
	s_barrier
	s_waitcnt lgkmcnt(0)
	s_waitcnt lgkmcnt(0)
	v_mfma_f32_16x16x32_bf16 v[60:63], v[146:149], v[162:165], v[60:63]
	v_mfma_f32_16x16x32_bf16 v[56:59], v[154:157], v[162:165], v[56:59]
	v_mfma_f32_16x16x32_bf16 v[44:47], v[146:149], v[170:173], v[44:47]
	v_mfma_f32_16x16x32_bf16 v[40:43], v[154:157], v[170:173], v[40:43]
	v_mfma_f32_16x16x32_bf16 v[28:31], v[146:149], v[178:181], v[28:31]
	v_mfma_f32_16x16x32_bf16 v[24:27], v[154:157], v[178:181], v[24:27]
	v_mfma_f32_16x16x32_bf16 v[12:15], v[146:149], v[186:189], v[12:15]
	v_mfma_f32_16x16x32_bf16 v[8:11], v[154:157], v[186:189], v[8:11]
	v_mfma_f32_16x16x32_bf16 v[60:63], v[150:153], v[166:169], v[60:63]
	v_mfma_f32_16x16x32_bf16 v[56:59], v[158:161], v[166:169], v[56:59]
	v_mfma_f32_16x16x32_bf16 v[44:47], v[150:153], v[174:177], v[44:47]
	v_mfma_f32_16x16x32_bf16 v[40:43], v[158:161], v[174:177], v[40:43]
	v_mfma_f32_16x16x32_bf16 v[28:31], v[150:153], v[182:185], v[28:31]
	v_mfma_f32_16x16x32_bf16 v[24:27], v[158:161], v[182:185], v[24:27]
	v_mfma_f32_16x16x32_bf16 v[12:15], v[150:153], v[190:193], v[12:15]
	v_mfma_f32_16x16x32_bf16 v[8:11], v[158:161], v[190:193], v[8:11]
	s_barrier
	ds_read_b128 v[146:149], v203
	ds_read_b128 v[150:153], v203 offset:1024
	ds_read_b128 v[154:157], v203 offset:2048
	ds_read_b128 v[158:161], v203 offset:3072
	s_add_u32 s20, s24, 0xb0080
	s_addc_u32 s21, s25, 0
	s_add_i32 s24, s26, s36
	s_mov_b32 m0, s24
	s_nop 0
	global_load_lds_dwordx4 v130, s[20:21]
	s_add_i32 m0, s24, 0x2000
	s_nop 0
	global_load_lds_dwordx4 v134, s[20:21]
	s_waitcnt vmcnt(8)
	s_barrier
	v_mfma_f32_16x16x32_bf16 v[52:55], v[194:197], v[162:165], v[52:55]
	v_mfma_f32_16x16x32_bf16 v[48:51], v[212:215], v[162:165], v[48:51]
	v_mfma_f32_16x16x32_bf16 v[36:39], v[194:197], v[170:173], v[36:39]
	v_mfma_f32_16x16x32_bf16 v[32:35], v[212:215], v[170:173], v[32:35]
	v_mfma_f32_16x16x32_bf16 v[20:23], v[194:197], v[178:181], v[20:23]
	v_mfma_f32_16x16x32_bf16 v[16:19], v[212:215], v[178:181], v[16:19]
	v_mfma_f32_16x16x32_bf16 v[4:7], v[194:197], v[186:189], v[4:7]
	v_mfma_f32_16x16x32_bf16 v[0:3], v[212:215], v[186:189], v[0:3]
	v_mfma_f32_16x16x32_bf16 v[52:55], v[208:211], v[166:169], v[52:55]
	v_mfma_f32_16x16x32_bf16 v[48:51], v[216:219], v[166:169], v[48:51]
	v_mfma_f32_16x16x32_bf16 v[36:39], v[208:211], v[174:177], v[36:39]
	v_mfma_f32_16x16x32_bf16 v[32:35], v[216:219], v[174:177], v[32:35]
	v_mfma_f32_16x16x32_bf16 v[20:23], v[208:211], v[182:185], v[20:23]
	v_mfma_f32_16x16x32_bf16 v[16:19], v[216:219], v[182:185], v[16:19]
	v_mfma_f32_16x16x32_bf16 v[4:7], v[208:211], v[190:193], v[4:7]
	v_mfma_f32_16x16x32_bf16 v[0:3], v[216:219], v[190:193], v[0:3]
	s_add_i32 s56, s56, 2
	s_add_u32 s54, s54, 0x100
	s_addc_u32 s55, s55, 0
	s_cmp_gt_u32 s56, 41
	s_mov_b64 s[20:21], s[22:23]
	s_barrier
	s_cbranch_scc0 .LBB0_973
	s_waitcnt lgkmcnt(0)
	s_setprio 0
	s_cmpk_gt_u32 s30, 0xff
	s_cbranch_scc1 .Lg973_nox
	s_barrier
	s_setprio 1
